# retention item epilogue: the 8 per-chunk gate loads issued together with the first (no load-after-store chain)
# speedup vs baseline: 1.0122x; 1.0005x over previous
.LBB0_1269:
	v_mov_b32_e32 v6, v74
	v_mov_b32_e32 v7, v78
	v_mov_b32_e32 v8, v75
	v_mov_b32_e32 v9, v79
	v_pk_add_f32 v[6:7], v[6:7], v[8:9]
	v_mov_b32_e32 v8, v76
	v_mov_b32_e32 v9, v80
	v_pk_add_f32 v[6:7], v[8:9], v[6:7]
	v_mov_b32_e32 v8, v77
	v_mov_b32_e32 v9, v81
	v_pk_add_f32 v[6:7], v[8:9], v[6:7]
	v_mov_b32_e32 v8, v71
	v_add_f32_e32 v4, 0, v6
	v_add_f32_e32 v4, v4, v7
	v_mov_b32_e32 v6, v70
	v_mov_b32_e32 v7, v66
	v_mov_b32_e32 v9, v67
	v_pk_add_f32 v[6:7], v[6:7], v[8:9]
	v_mov_b32_e32 v8, v72
	v_mov_b32_e32 v9, v68
	v_pk_add_f32 v[6:7], v[8:9], v[6:7]
	v_mov_b32_e32 v8, v73
	v_mov_b32_e32 v9, v69
	v_pk_add_f32 v[6:7], v[8:9], v[6:7]
	v_mov_b32_e32 v8, v63
	v_add_f32_e32 v4, v4, v6
	v_add_f32_e32 v4, v4, v7
	v_mov_b32_e32 v6, v62
	v_mov_b32_e32 v7, v58
	v_mov_b32_e32 v9, v59
	v_pk_add_f32 v[6:7], v[6:7], v[8:9]
	v_mov_b32_e32 v8, v64
	v_mov_b32_e32 v9, v60
	v_pk_add_f32 v[6:7], v[8:9], v[6:7]
	v_mov_b32_e32 v8, v65
	v_mov_b32_e32 v9, v61
	v_pk_add_f32 v[6:7], v[8:9], v[6:7]
	v_mov_b32_e32 v8, v55
	v_add_f32_e32 v4, v4, v6
	v_add_f32_e32 v4, v4, v7
	v_mov_b32_e32 v6, v54
	v_mov_b32_e32 v7, v0
	v_mov_b32_e32 v9, v1
	v_pk_add_f32 v[6:7], v[6:7], v[8:9]
	v_mov_b32_e32 v8, v56
	v_mov_b32_e32 v9, v2
	v_pk_add_f32 v[6:7], v[8:9], v[6:7]
	v_mov_b32_e32 v8, v57
	v_mov_b32_e32 v9, v3
	v_pk_add_f32 v[6:7], v[8:9], v[6:7]
	v_or3_b32 v110, v168, s9, v110
	v_add_f32_e32 v4, v4, v6
	v_add_f32_e32 v4, v4, v7
	v_and_b32_e32 v7, 64, v238
	v_xor_b32_e32 v6, 16, v238
	v_add_u32_e32 v12, 64, v7
	v_cmp_lt_i32_e32 vcc, v6, v12
	v_lshlrev_b64 v[8:9], 1, v[110:111]
	s_mov_b32 s0, 0x800000
	v_cndmask_b32_e32 v6, v238, v6, vcc
	v_lshlrev_b32_e32 v82, 2, v6
	v_lshl_add_u64 v[6:7], s[50:51], 0, v[8:9]
	global_load_dwordx2 v[10:11], v[6:7], off
	v_or_b32_e32 v222, 0x10, v110
	v_mov_b32_e32 v223, v111
	v_lshlrev_b64 v[222:223], 1, v[222:223]
	v_lshl_add_u64 v[222:223], s[50:51], 0, v[222:223]
	global_load_dwordx2 v[208:209], v[222:223], off
	v_or_b32_e32 v222, 0x20, v110
	v_mov_b32_e32 v223, v111
	v_lshlrev_b64 v[222:223], 1, v[222:223]
	v_lshl_add_u64 v[222:223], s[50:51], 0, v[222:223]
	global_load_dwordx2 v[210:211], v[222:223], off
	v_or_b32_e32 v222, 0x30, v110
	v_mov_b32_e32 v223, v111
	v_lshlrev_b64 v[222:223], 1, v[222:223]
	v_lshl_add_u64 v[222:223], s[50:51], 0, v[222:223]
	global_load_dwordx2 v[212:213], v[222:223], off
	v_or_b32_e32 v222, 0x40, v110
	v_mov_b32_e32 v223, v111
	v_lshlrev_b64 v[222:223], 1, v[222:223]
	v_lshl_add_u64 v[222:223], s[50:51], 0, v[222:223]
	global_load_dwordx2 v[214:215], v[222:223], off
	v_or_b32_e32 v222, 0x50, v110
	v_mov_b32_e32 v223, v111
	v_lshlrev_b64 v[222:223], 1, v[222:223]
	v_lshl_add_u64 v[222:223], s[50:51], 0, v[222:223]
	global_load_dwordx2 v[216:217], v[222:223], off
	v_or_b32_e32 v222, 0x60, v110
	v_mov_b32_e32 v223, v111
	v_lshlrev_b64 v[222:223], 1, v[222:223]
	v_lshl_add_u64 v[222:223], s[50:51], 0, v[222:223]
	global_load_dwordx2 v[218:219], v[222:223], off
	v_or_b32_e32 v222, 0x70, v110
	v_mov_b32_e32 v223, v111
	v_lshlrev_b64 v[222:223], 1, v[222:223]
	v_lshl_add_u64 v[222:223], s[50:51], 0, v[222:223]
	global_load_dwordx2 v[220:221], v[222:223], off
	ds_bpermute_b32 v13, v82, v4
	v_xor_b32_e32 v6, 32, v238
	v_cmp_lt_i32_e32 vcc, v6, v12
	v_lshl_add_u64 v[8:9], s[52:53], 0, v[8:9]
	s_waitcnt lgkmcnt(0)
	v_add_f32_e32 v4, v4, v13
	v_cndmask_b32_e32 v6, v238, v6, vcc
	v_lshlrev_b32_e32 v83, 2, v6
	ds_bpermute_b32 v6, v83, v4
	s_waitcnt lgkmcnt(0)
	v_add_f32_e32 v4, v4, v6
	v_mul_f32_e32 v4, 0x3c000000, v4
	v_pk_add_f32 v[18:19], v[74:75], v[4:5] op_sel_hi:[1,0] neg_lo:[0,1] neg_hi:[0,1]
	v_pk_add_f32 v[14:15], v[76:77], v[4:5] op_sel_hi:[1,0] neg_lo:[0,1] neg_hi:[0,1]
	v_pk_mul_f32 v[20:21], v[18:19], v[18:19]
	v_pk_add_f32 v[6:7], v[0:1], v[4:5] op_sel_hi:[1,0] neg_lo:[0,1] neg_hi:[0,1]
	v_pk_add_f32 v[0:1], v[2:3], v[4:5] op_sel_hi:[1,0] neg_lo:[0,1] neg_hi:[0,1]
	v_pk_mul_f32 v[16:17], v[14:15], v[14:15]
	s_waitcnt vmcnt(8)
	v_pk_add_f32 v[22:23], v[80:81], v[4:5] op_sel_hi:[1,0] neg_lo:[0,1] neg_hi:[0,1]
	s_waitcnt vmcnt(7)
	v_pk_add_f32 v[26:27], v[78:79], v[4:5] op_sel_hi:[1,0] neg_lo:[0,1] neg_hi:[0,1]
	s_waitcnt vmcnt(6)
	v_pk_add_f32 v[30:31], v[72:73], v[4:5] op_sel_hi:[1,0] neg_lo:[0,1] neg_hi:[0,1]
	s_waitcnt vmcnt(5)
	v_pk_add_f32 v[34:35], v[70:71], v[4:5] op_sel_hi:[1,0] neg_lo:[0,1] neg_hi:[0,1]
	s_waitcnt vmcnt(4)
	v_pk_add_f32 v[38:39], v[68:69], v[4:5] op_sel_hi:[1,0] neg_lo:[0,1] neg_hi:[0,1]
	s_waitcnt vmcnt(3)
	v_pk_add_f32 v[42:43], v[66:67], v[4:5] op_sel_hi:[1,0] neg_lo:[0,1] neg_hi:[0,1]
	s_waitcnt vmcnt(2)
	v_pk_add_f32 v[46:47], v[64:65], v[4:5] op_sel_hi:[1,0] neg_lo:[0,1] neg_hi:[0,1]
	s_waitcnt vmcnt(1)
	v_pk_add_f32 v[50:51], v[62:63], v[4:5] op_sel_hi:[1,0] neg_lo:[0,1] neg_hi:[0,1]
	v_pk_add_f32 v[60:61], v[60:61], v[4:5] op_sel_hi:[1,0] neg_lo:[0,1] neg_hi:[0,1]
	v_pk_add_f32 v[58:59], v[58:59], v[4:5] op_sel_hi:[1,0] neg_lo:[0,1] neg_hi:[0,1]
	v_pk_add_f32 v[56:57], v[56:57], v[4:5] op_sel_hi:[1,0] neg_lo:[0,1] neg_hi:[0,1]
	v_pk_add_f32 v[54:55], v[54:55], v[4:5] op_sel_hi:[1,0] neg_lo:[0,1] neg_hi:[0,1]
	v_add_f32_e32 v4, v20, v21
	v_add_f32_e32 v4, v16, v4
	v_pk_mul_f32 v[28:29], v[26:27], v[26:27]
	v_add_f32_e32 v4, v17, v4
	v_add_f32_e32 v4, v28, v4
	v_pk_mul_f32 v[24:25], v[22:23], v[22:23]
	v_add_f32_e32 v4, v29, v4
	v_add_f32_e32 v4, v24, v4
	v_pk_mul_f32 v[36:37], v[34:35], v[34:35]
	v_add_f32_e32 v4, v25, v4
	v_add_f32_e32 v4, v36, v4
	v_pk_mul_f32 v[32:33], v[30:31], v[30:31]
	v_add_f32_e32 v4, v37, v4
	v_add_f32_e32 v4, v32, v4
	v_pk_mul_f32 v[44:45], v[42:43], v[42:43]
	v_add_f32_e32 v4, v33, v4
	v_add_f32_e32 v4, v44, v4
	v_pk_mul_f32 v[40:41], v[38:39], v[38:39]
	v_add_f32_e32 v4, v45, v4
	v_add_f32_e32 v4, v40, v4
	v_pk_mul_f32 v[52:53], v[50:51], v[50:51]
	v_add_f32_e32 v4, v41, v4
	v_add_f32_e32 v4, v52, v4
	v_pk_mul_f32 v[48:49], v[46:47], v[46:47]
	v_add_f32_e32 v4, v53, v4
	v_add_f32_e32 v4, v48, v4
	v_pk_mul_f32 v[64:65], v[58:59], v[58:59]
	v_add_f32_e32 v4, v49, v4
	v_add_f32_e32 v4, v64, v4
	v_pk_mul_f32 v[62:63], v[60:61], v[60:61]
	v_add_f32_e32 v4, v65, v4
	v_add_f32_e32 v4, v62, v4
	v_pk_mul_f32 v[68:69], v[54:55], v[54:55]
	v_add_f32_e32 v4, v63, v4
	v_add_f32_e32 v4, v68, v4
	v_pk_mul_f32 v[66:67], v[56:57], v[56:57]
	v_add_f32_e32 v4, v69, v4
	v_add_f32_e32 v4, v66, v4
	v_pk_mul_f32 v[12:13], v[6:7], v[6:7]
	v_add_f32_e32 v4, v67, v4
	v_add_f32_e32 v4, v12, v4
	v_pk_mul_f32 v[2:3], v[0:1], v[0:1]
	v_add_f32_e32 v4, v13, v4
	v_add_f32_e32 v2, v2, v4
	v_add_f32_e32 v4, v3, v2
	ds_bpermute_b32 v12, v82, v4
	s_waitcnt vmcnt(0)
	v_lshlrev_b32_e32 v2, 16, v10
	v_and_b32_e32 v3, 0xffff0000, v10
	v_lshlrev_b32_e32 v10, 16, v11
	v_and_b32_e32 v11, 0xffff0000, v11
	s_waitcnt lgkmcnt(0)
	v_add_f32_e32 v4, v4, v12
	ds_bpermute_b32 v13, v83, v4
	v_or_b32_e32 v12, 16, v110
	s_waitcnt lgkmcnt(0)
	v_add_f32_e32 v4, v4, v13
	v_fmamk_f32 v4, v4, 0x3c000000, v236
	v_mul_f32_e32 v13, 0x4b800000, v4
	v_cmp_gt_f32_e32 vcc, s0, v4
	s_nop 1
	v_cndmask_b32_e32 v4, v4, v13, vcc
	v_rsq_f32_e32 v4, v4
	v_mov_b32_e32 v13, v111
	v_lshlrev_b64 v[12:13], 1, v[12:13]
	v_lshl_add_u64 v[16:17], s[50:51], 0, v[12:13]
	v_mul_f32_e32 v20, 0x45800000, v4
	v_cndmask_b32_e32 v4, v4, v20, vcc
	v_pk_mul_f32 v[18:19], v[18:19], v[4:5] op_sel_hi:[1,0]
	v_pk_mul_f32 v[14:15], v[14:15], v[4:5] op_sel_hi:[1,0]
	v_pk_mul_f32 v[2:3], v[18:19], v[2:3]
	v_pk_mul_f32 v[10:11], v[14:15], v[10:11]
	v_cvt_pk_bf16_f32 v2, v2, v3
	v_cvt_pk_bf16_f32 v3, v10, v11
	global_store_dwordx2 v[8:9], v[2:3], off
	v_mov_b64_e32 v[2:3], v[208:209]
	v_pk_mul_f32 v[16:17], v[26:27], v[4:5] op_sel_hi:[1,0]
	v_mov_b32_e32 v9, v111
	v_or_b32_e32 v8, 32, v110
	v_lshlrev_b64 v[8:9], 1, v[8:9]
	v_lshl_add_u64 v[10:11], s[52:53], 0, v[12:13]
	v_lshl_add_u64 v[12:13], s[50:51], 0, v[8:9]
	v_lshl_add_u64 v[8:9], s[52:53], 0, v[8:9]
	v_pk_mul_f32 v[6:7], v[6:7], v[4:5] op_sel_hi:[1,0]
	v_pk_mul_f32 v[0:1], v[0:1], v[4:5] op_sel_hi:[1,0]
	v_lshlrev_b32_e32 v14, 16, v2
	v_and_b32_e32 v15, 0xffff0000, v2
	v_pk_mul_f32 v[14:15], v[16:17], v[14:15]
	v_lshlrev_b32_e32 v2, 16, v3
	v_pk_mul_f32 v[16:17], v[22:23], v[4:5] op_sel_hi:[1,0]
	v_and_b32_e32 v3, 0xffff0000, v3
	v_pk_mul_f32 v[2:3], v[16:17], v[2:3]
	v_cvt_pk_bf16_f32 v14, v14, v15
	v_cvt_pk_bf16_f32 v15, v2, v3
	global_store_dwordx2 v[10:11], v[14:15], off
	v_mov_b64_e32 v[2:3], v[210:211]
	v_pk_mul_f32 v[14:15], v[34:35], v[4:5] op_sel_hi:[1,0]
	v_pk_mul_f32 v[16:17], v[30:31], v[4:5] op_sel_hi:[1,0]
	v_mov_b32_e32 v11, v111
	v_or_b32_e32 v10, 48, v110
	v_lshlrev_b64 v[10:11], 1, v[10:11]
	v_lshl_add_u64 v[12:13], s[50:51], 0, v[10:11]
	v_lshl_add_u64 v[10:11], s[52:53], 0, v[10:11]
	v_lshlrev_b32_e32 v18, 16, v2
	v_and_b32_e32 v19, 0xffff0000, v2
	v_lshlrev_b32_e32 v2, 16, v3
	v_and_b32_e32 v3, 0xffff0000, v3
	v_pk_mul_f32 v[14:15], v[14:15], v[18:19]
	v_pk_mul_f32 v[2:3], v[16:17], v[2:3]
	v_cvt_pk_bf16_f32 v14, v14, v15
	v_cvt_pk_bf16_f32 v15, v2, v3
	global_store_dwordx2 v[8:9], v[14:15], off
	v_mov_b64_e32 v[2:3], v[212:213]
	v_pk_mul_f32 v[14:15], v[42:43], v[4:5] op_sel_hi:[1,0]
	v_pk_mul_f32 v[16:17], v[38:39], v[4:5] op_sel_hi:[1,0]
	v_mov_b32_e32 v9, v111
	v_or_b32_e32 v8, 64, v110
	v_lshlrev_b64 v[8:9], 1, v[8:9]
	v_lshl_add_u64 v[12:13], s[50:51], 0, v[8:9]
	v_lshl_add_u64 v[8:9], s[52:53], 0, v[8:9]
	v_lshlrev_b32_e32 v18, 16, v2
	v_and_b32_e32 v19, 0xffff0000, v2
	v_lshlrev_b32_e32 v2, 16, v3
	v_and_b32_e32 v3, 0xffff0000, v3
	v_pk_mul_f32 v[14:15], v[14:15], v[18:19]
	v_pk_mul_f32 v[2:3], v[16:17], v[2:3]
	v_cvt_pk_bf16_f32 v14, v14, v15
	v_cvt_pk_bf16_f32 v15, v2, v3
	global_store_dwordx2 v[10:11], v[14:15], off
	v_mov_b64_e32 v[2:3], v[214:215]
	v_pk_mul_f32 v[14:15], v[50:51], v[4:5] op_sel_hi:[1,0]
	v_pk_mul_f32 v[16:17], v[46:47], v[4:5] op_sel_hi:[1,0]
	v_mov_b32_e32 v11, v111
	v_or_b32_e32 v10, 0x50, v110
	v_lshlrev_b64 v[10:11], 1, v[10:11]
	v_lshl_add_u64 v[12:13], s[50:51], 0, v[10:11]
	v_lshl_add_u64 v[10:11], s[52:53], 0, v[10:11]
	v_lshlrev_b32_e32 v18, 16, v2
	v_and_b32_e32 v19, 0xffff0000, v2
	v_lshlrev_b32_e32 v2, 16, v3
	v_and_b32_e32 v3, 0xffff0000, v3
	v_pk_mul_f32 v[14:15], v[14:15], v[18:19]
	v_pk_mul_f32 v[2:3], v[16:17], v[2:3]
	v_cvt_pk_bf16_f32 v14, v14, v15
	v_cvt_pk_bf16_f32 v15, v2, v3
	global_store_dwordx2 v[8:9], v[14:15], off
	v_mov_b64_e32 v[2:3], v[216:217]
	v_pk_mul_f32 v[14:15], v[58:59], v[4:5] op_sel_hi:[1,0]
	v_pk_mul_f32 v[16:17], v[60:61], v[4:5] op_sel_hi:[1,0]
	v_mov_b32_e32 v9, v111
	v_or_b32_e32 v8, 0x60, v110
	v_lshlrev_b64 v[8:9], 1, v[8:9]
	v_lshl_add_u64 v[12:13], s[50:51], 0, v[8:9]
	v_or_b32_e32 v110, 0x70, v110
	v_lshl_add_u64 v[8:9], s[52:53], 0, v[8:9]
	v_lshlrev_b32_e32 v18, 16, v2
	v_and_b32_e32 v19, 0xffff0000, v2
	v_lshlrev_b32_e32 v2, 16, v3
	v_and_b32_e32 v3, 0xffff0000, v3
	v_pk_mul_f32 v[14:15], v[14:15], v[18:19]
	v_pk_mul_f32 v[2:3], v[16:17], v[2:3]
	v_cvt_pk_bf16_f32 v14, v14, v15
	v_cvt_pk_bf16_f32 v15, v2, v3
	global_store_dwordx2 v[10:11], v[14:15], off
	v_mov_b64_e32 v[2:3], v[218:219]
	v_pk_mul_f32 v[14:15], v[54:55], v[4:5] op_sel_hi:[1,0]
	v_pk_mul_f32 v[16:17], v[56:57], v[4:5] op_sel_hi:[1,0]
	v_lshlrev_b64 v[10:11], 1, v[110:111]
	v_lshl_add_u64 v[12:13], s[50:51], 0, v[10:11]
	v_lshlrev_b32_e32 v18, 16, v2
	v_and_b32_e32 v19, 0xffff0000, v2
	v_lshlrev_b32_e32 v2, 16, v3
	v_and_b32_e32 v3, 0xffff0000, v3
	v_pk_mul_f32 v[14:15], v[14:15], v[18:19]
	v_pk_mul_f32 v[2:3], v[16:17], v[2:3]
	v_cvt_pk_bf16_f32 v14, v14, v15
	v_cvt_pk_bf16_f32 v15, v2, v3
	global_store_dwordx2 v[8:9], v[14:15], off
	v_mov_b64_e32 v[2:3], v[220:221]
	v_lshlrev_b32_e32 v8, 16, v2
	v_and_b32_e32 v9, 0xffff0000, v2
	v_lshlrev_b32_e32 v2, 16, v3
	v_and_b32_e32 v3, 0xffff0000, v3
	v_pk_mul_f32 v[6:7], v[6:7], v[8:9]
	v_pk_mul_f32 v[0:1], v[0:1], v[2:3]
	v_cvt_pk_bf16_f32 v2, v6, v7
	v_cvt_pk_bf16_f32 v3, v0, v1
	v_lshl_add_u64 v[0:1], s[52:53], 0, v[10:11]
	global_store_dwordx2 v[0:1], v[2:3], off

.LBB0_1554:
	s_or_b32 s46, s5, s4
	v_cndmask_b32_e64 v100, v98, v99, s[0:1]
	s_lshl_b64 s[6:7], s[46:47], 15
	v_lshl_add_u64 v[96:97], v[50:51], 0, s[6:7]
	v_pk_mul_f32 v[14:15], v[100:101], v[52:53] op_sel_hi:[0,1]
	v_pk_mul_f32 v[16:17], v[100:101], v[38:39] op_sel_hi:[0,1]
	v_cvt_pk_bf16_f32 v14, v14, v15
	v_cvt_pk_bf16_f32 v15, v16, v17
	v_pk_mul_f32 v[16:17], v[100:101], v[54:55] op_sel_hi:[0,1]
	v_pk_mul_f32 v[18:19], v[100:101], v[40:41] op_sel_hi:[0,1]
	v_lshl_add_u64 v[94:95], v[96:97], 0, v[4:5]
	v_cvt_pk_bf16_f32 v16, v16, v17
	v_cvt_pk_bf16_f32 v17, v18, v19
	global_load_dwordx4 v[144:147], v[94:95], off
	v_lshl_add_u64 v[178:179], v[96:97], 0, v[56:57]
	global_load_dwordx4 v[148:151], v[178:179], off
	v_lshl_add_u64 v[180:181], v[96:97], 0, v[60:61]
	global_load_dwordx4 v[152:155], v[180:181], off
	v_lshl_add_u64 v[182:183], v[96:97], 0, v[58:59]
	global_load_dwordx4 v[156:159], v[182:183], off
	v_lshl_add_u64 v[184:185], v[96:97], 0, v[62:63]
	global_load_dwordx4 v[160:163], v[184:185], off
	v_lshl_add_u64 v[186:187], v[96:97], 0, v[66:67]
	global_load_dwordx4 v[164:167], v[186:187], off
	v_lshl_add_u64 v[188:189], v[96:97], 0, v[64:65]
	global_load_dwordx4 v[168:171], v[188:189], off
	v_lshl_add_u64 v[190:191], v[96:97], 0, v[68:69]
	global_load_dwordx4 v[172:175], v[190:191], off
	s_mov_b64 s[6:7], 0xc0
	s_mov_b32 s5, 4
	s_and_b64 vcc, exec, s[0:1]
	s_mov_b64 s[0:1], 0
	s_waitcnt vmcnt(7)
	v_mfma_f32_16x16x32_bf16 v[6:9], v[144:147], v[14:17], v[6:9]
	s_nop 0
	s_waitcnt vmcnt(6)
	v_mfma_f32_16x16x32_bf16 v[10:13], v[148:151], v[14:17], v[10:13]
	s_waitcnt vmcnt(5)
	v_mfma_f32_16x16x32_bf16 v[26:29], v[152:155], v[14:17], v[26:29]
	s_waitcnt vmcnt(4)
	v_mfma_f32_16x16x32_bf16 v[18:21], v[156:159], v[14:17], v[34:37]
	s_nop 2
	s_waitcnt vmcnt(3)
	v_mfma_f32_16x16x32_bf16 v[22:25], v[160:163], v[14:17], v[22:25]
	s_waitcnt vmcnt(2)
	v_mfma_f32_16x16x32_bf16 v[34:37], v[164:167], v[14:17], v[42:45]
	s_nop 2
	s_waitcnt vmcnt(1)
	v_mfma_f32_16x16x32_bf16 v[30:33], v[168:171], v[14:17], v[46:49]
	s_nop 2
	v_lshl_add_u64 v[46:47], v[96:97], 0, 64
	s_waitcnt vmcnt(0)
	v_mfma_f32_16x16x32_bf16 v[0:3], v[172:175], v[14:17], v[0:3]
	v_mul_f32_e64 v14, v100, v70
	v_mul_f32_e64 v15, v100, v71
	v_pk_mul_f32 v[16:17], v[100:101], v[72:73] op_sel_hi:[0,1]
	v_cvt_pk_bf16_f32 v14, v14, v15
	v_cvt_pk_bf16_f32 v15, v16, v17
	v_pk_mul_f32 v[16:17], v[100:101], v[74:75] op_sel_hi:[0,1]
	v_pk_mul_f32 v[42:43], v[100:101], v[76:77] op_sel_hi:[0,1]
	v_cvt_pk_bf16_f32 v16, v16, v17
	v_cvt_pk_bf16_f32 v17, v42, v43
	global_load_dwordx4 v[144:147], v[94:95], off offset:64
	v_lshl_add_u64 v[178:179], v[46:47], 0, v[56:57]
	global_load_dwordx4 v[148:151], v[178:179], off
	v_lshl_add_u64 v[180:181], v[46:47], 0, v[58:59]
	global_load_dwordx4 v[152:155], v[180:181], off
	v_lshl_add_u64 v[182:183], v[46:47], 0, v[60:61]
	global_load_dwordx4 v[156:159], v[182:183], off
	v_lshl_add_u64 v[184:185], v[46:47], 0, v[62:63]
	global_load_dwordx4 v[160:163], v[184:185], off
	v_lshl_add_u64 v[186:187], v[46:47], 0, v[64:65]
	global_load_dwordx4 v[164:167], v[186:187], off
	v_lshl_add_u64 v[188:189], v[46:47], 0, v[66:67]
	global_load_dwordx4 v[168:171], v[188:189], off
	v_lshl_add_u64 v[190:191], v[46:47], 0, v[68:69]
	global_load_dwordx4 v[172:175], v[190:191], off
	s_waitcnt vmcnt(7)
	v_mfma_f32_16x16x32_bf16 v[6:9], v[144:147], v[14:17], v[6:9]
	s_waitcnt vmcnt(6)
	v_mfma_f32_16x16x32_bf16 v[10:13], v[148:151], v[14:17], v[10:13]
	s_waitcnt vmcnt(5)
	v_mfma_f32_16x16x32_bf16 v[18:21], v[152:155], v[14:17], v[18:21]
	s_waitcnt vmcnt(4)
	v_mfma_f32_16x16x32_bf16 v[26:29], v[156:159], v[14:17], v[26:29]
	s_waitcnt vmcnt(3)
	v_mfma_f32_16x16x32_bf16 v[22:25], v[160:163], v[14:17], v[22:25]
	s_waitcnt vmcnt(2)
	v_mfma_f32_16x16x32_bf16 v[30:33], v[164:167], v[14:17], v[30:33]
	s_waitcnt vmcnt(1)
	v_mfma_f32_16x16x32_bf16 v[42:45], v[168:171], v[14:17], v[34:37]
	s_nop 2
	v_lshl_add_u64 v[46:47], v[96:97], 0, s[44:45]
	v_lshl_add_u64 v[96:97], v[96:97], 0, s[6:7]
	s_waitcnt vmcnt(0)
	v_mfma_f32_16x16x32_bf16 v[0:3], v[172:175], v[14:17], v[0:3]
	v_mul_f32_e64 v14, v100, v78
	v_mul_f32_e64 v15, v100, v79
	v_pk_mul_f32 v[16:17], v[100:101], v[80:81] op_sel_hi:[0,1]
	v_cvt_pk_bf16_f32 v14, v14, v15
	v_cvt_pk_bf16_f32 v15, v16, v17
	v_pk_mul_f32 v[16:17], v[100:101], v[82:83] op_sel_hi:[0,1]
	v_pk_mul_f32 v[34:35], v[100:101], v[84:85] op_sel_hi:[0,1]
	v_cvt_pk_bf16_f32 v16, v16, v17
	v_cvt_pk_bf16_f32 v17, v34, v35
	global_load_dwordx4 v[144:147], v[94:95], off offset:128
	v_lshl_add_u64 v[178:179], v[46:47], 0, v[56:57]
	global_load_dwordx4 v[148:151], v[178:179], off
	v_lshl_add_u64 v[180:181], v[46:47], 0, v[58:59]
	global_load_dwordx4 v[152:155], v[180:181], off
	v_lshl_add_u64 v[182:183], v[46:47], 0, v[60:61]
	global_load_dwordx4 v[156:159], v[182:183], off
	v_lshl_add_u64 v[184:185], v[46:47], 0, v[62:63]
	global_load_dwordx4 v[160:163], v[184:185], off
	v_lshl_add_u64 v[186:187], v[46:47], 0, v[64:65]
	global_load_dwordx4 v[164:167], v[186:187], off
	v_lshl_add_u64 v[188:189], v[46:47], 0, v[66:67]
	global_load_dwordx4 v[168:171], v[188:189], off
	v_lshl_add_u64 v[190:191], v[46:47], 0, v[68:69]
	global_load_dwordx4 v[172:175], v[190:191], off
	s_waitcnt vmcnt(7)
	v_mfma_f32_16x16x32_bf16 v[6:9], v[144:147], v[14:17], v[6:9]
	s_waitcnt vmcnt(6)
	v_mfma_f32_16x16x32_bf16 v[10:13], v[148:151], v[14:17], v[10:13]
	s_waitcnt vmcnt(5)
	v_mfma_f32_16x16x32_bf16 v[34:37], v[152:155], v[14:17], v[18:21]
	s_nop 2
	s_waitcnt vmcnt(4)
	v_mfma_f32_16x16x32_bf16 v[26:29], v[156:159], v[14:17], v[26:29]
	s_waitcnt vmcnt(3)
	v_mfma_f32_16x16x32_bf16 v[22:25], v[160:163], v[14:17], v[22:25]
	s_waitcnt vmcnt(2)
	v_mfma_f32_16x16x32_bf16 v[30:33], v[164:167], v[14:17], v[30:33]
	s_waitcnt vmcnt(1)
	v_mfma_f32_16x16x32_bf16 v[18:21], v[168:171], v[14:17], v[42:45]
	s_nop 2
	s_waitcnt vmcnt(0)
	v_mfma_f32_16x16x32_bf16 v[0:3], v[172:175], v[14:17], v[0:3]
	v_mul_f32_e64 v14, v100, v86
	v_mul_f32_e64 v15, v100, v87
	v_pk_mul_f32 v[16:17], v[100:101], v[88:89] op_sel_hi:[0,1]
	v_cvt_pk_bf16_f32 v14, v14, v15
	v_cvt_pk_bf16_f32 v15, v16, v17
	v_pk_mul_f32 v[16:17], v[100:101], v[90:91] op_sel_hi:[0,1]
	v_pk_mul_f32 v[42:43], v[100:101], v[92:93] op_sel_hi:[0,1]
	v_cvt_pk_bf16_f32 v16, v16, v17
	v_cvt_pk_bf16_f32 v17, v42, v43
	global_load_dwordx4 v[144:147], v[94:95], off offset:192
	v_lshl_add_u64 v[178:179], v[96:97], 0, v[56:57]
	global_load_dwordx4 v[148:151], v[178:179], off
	v_lshl_add_u64 v[180:181], v[96:97], 0, v[58:59]
	global_load_dwordx4 v[152:155], v[180:181], off
	v_lshl_add_u64 v[182:183], v[96:97], 0, v[60:61]
	global_load_dwordx4 v[156:159], v[182:183], off
	v_lshl_add_u64 v[184:185], v[96:97], 0, v[62:63]
	global_load_dwordx4 v[160:163], v[184:185], off
	v_lshl_add_u64 v[186:187], v[96:97], 0, v[64:65]
	global_load_dwordx4 v[164:167], v[186:187], off
	v_lshl_add_u64 v[188:189], v[96:97], 0, v[66:67]
	global_load_dwordx4 v[168:171], v[188:189], off
	v_lshl_add_u64 v[190:191], v[96:97], 0, v[68:69]
	global_load_dwordx4 v[172:175], v[190:191], off
	s_waitcnt vmcnt(7)
	v_mfma_f32_16x16x32_bf16 v[6:9], v[144:147], v[14:17], v[6:9]
	s_waitcnt vmcnt(6)
	v_mfma_f32_16x16x32_bf16 v[10:13], v[148:151], v[14:17], v[10:13]
	s_waitcnt vmcnt(5)
	v_mfma_f32_16x16x32_bf16 v[34:37], v[152:155], v[14:17], v[34:37]
	s_waitcnt vmcnt(4)
	v_mfma_f32_16x16x32_bf16 v[26:29], v[156:159], v[14:17], v[26:29]
	s_waitcnt vmcnt(3)
	v_mfma_f32_16x16x32_bf16 v[22:25], v[160:163], v[14:17], v[22:25]
	s_waitcnt vmcnt(2)
	v_mfma_f32_16x16x32_bf16 v[46:49], v[164:167], v[14:17], v[30:33]
	s_nop 2
	s_waitcnt vmcnt(1)
	v_mfma_f32_16x16x32_bf16 v[42:45], v[168:171], v[14:17], v[18:21]
	s_nop 2
	s_waitcnt vmcnt(0)
	v_mfma_f32_16x16x32_bf16 v[0:3], v[172:175], v[14:17], v[0:3]
	s_cbranch_vccnz .LBB0_1554
	v_mov_b32_e32 v14, v6
	v_mov_b32_e32 v15, v10
	v_mov_b32_e32 v16, v7
	v_mov_b32_e32 v17, v11
	v_pk_add_f32 v[14:15], v[14:15], v[16:17]
	v_mov_b32_e32 v16, v8
	v_mov_b32_e32 v17, v12
	v_pk_add_f32 v[14:15], v[16:17], v[14:15]
	v_mov_b32_e32 v16, v9
	v_mov_b32_e32 v17, v13
	v_pk_add_f32 v[14:15], v[16:17], v[14:15]
	v_mov_b32_e32 v16, v35
	v_add_f32_e32 v4, 0, v14
	v_add_f32_e32 v4, v4, v15
	v_mov_b32_e32 v14, v34
	v_mov_b32_e32 v15, v26
	v_mov_b32_e32 v17, v27
	v_pk_add_f32 v[14:15], v[14:15], v[16:17]
	v_mov_b32_e32 v16, v36
	v_mov_b32_e32 v17, v28
	v_pk_add_f32 v[14:15], v[16:17], v[14:15]
	v_mov_b32_e32 v16, v37
	v_mov_b32_e32 v17, v29
	v_pk_add_f32 v[14:15], v[16:17], v[14:15]
	v_mov_b32_e32 v16, v23
	v_add_f32_e32 v4, v4, v14
	v_add_f32_e32 v4, v4, v15
	v_mov_b32_e32 v14, v22
	v_mov_b32_e32 v15, v46
	v_mov_b32_e32 v17, v47
	v_pk_add_f32 v[14:15], v[14:15], v[16:17]
	v_mov_b32_e32 v16, v24
	v_mov_b32_e32 v17, v48
	v_pk_add_f32 v[14:15], v[16:17], v[14:15]
	v_mov_b32_e32 v16, v25
	v_mov_b32_e32 v17, v49
	v_pk_add_f32 v[14:15], v[16:17], v[14:15]
	v_mov_b32_e32 v16, v43
	v_add_f32_e32 v4, v4, v14
	v_add_f32_e32 v4, v4, v15
	v_mov_b32_e32 v14, v42
	v_mov_b32_e32 v15, v0
	v_mov_b32_e32 v17, v1
	v_pk_add_f32 v[14:15], v[14:15], v[16:17]
	v_mov_b32_e32 v16, v44
	v_mov_b32_e32 v17, v2
	v_pk_add_f32 v[14:15], v[16:17], v[14:15]
	v_mov_b32_e32 v16, v45
	v_mov_b32_e32 v17, v3
	v_pk_add_f32 v[14:15], v[16:17], v[14:15]
	v_or3_b32 v110, v141, s2, v110
	v_add_f32_e32 v4, v4, v14
	v_add_f32_e32 v4, v4, v15
	v_and_b32_e32 v15, 64, v238
	v_xor_b32_e32 v14, 16, v238
	v_add_u32_e32 v20, 64, v15
	v_cmp_lt_i32_e32 vcc, v14, v20
	v_lshlrev_b64 v[16:17], 1, v[110:111]
	s_mov_b32 s0, 0x800000
	v_cndmask_b32_e32 v14, v238, v14, vcc
	v_lshlrev_b32_e32 v70, 2, v14
	v_lshl_add_u64 v[14:15], s[50:51], 0, v[16:17]
	global_load_dwordx2 v[18:19], v[14:15], off
	v_or_b32_e32 v222, 0x10, v110
	v_mov_b32_e32 v223, v111
	v_lshlrev_b64 v[222:223], 1, v[222:223]
	v_lshl_add_u64 v[222:223], s[50:51], 0, v[222:223]
	global_load_dwordx2 v[208:209], v[222:223], off
	v_or_b32_e32 v222, 0x20, v110
	v_mov_b32_e32 v223, v111
	v_lshlrev_b64 v[222:223], 1, v[222:223]
	v_lshl_add_u64 v[222:223], s[50:51], 0, v[222:223]
	global_load_dwordx2 v[210:211], v[222:223], off
	v_or_b32_e32 v222, 0x30, v110
	v_mov_b32_e32 v223, v111
	v_lshlrev_b64 v[222:223], 1, v[222:223]
	v_lshl_add_u64 v[222:223], s[50:51], 0, v[222:223]
	global_load_dwordx2 v[212:213], v[222:223], off
	v_or_b32_e32 v222, 0x40, v110
	v_mov_b32_e32 v223, v111
	v_lshlrev_b64 v[222:223], 1, v[222:223]
	v_lshl_add_u64 v[222:223], s[50:51], 0, v[222:223]
	global_load_dwordx2 v[214:215], v[222:223], off
	v_or_b32_e32 v222, 0x50, v110
	v_mov_b32_e32 v223, v111
	v_lshlrev_b64 v[222:223], 1, v[222:223]
	v_lshl_add_u64 v[222:223], s[50:51], 0, v[222:223]
	global_load_dwordx2 v[216:217], v[222:223], off
	v_or_b32_e32 v222, 0x60, v110
	v_mov_b32_e32 v223, v111
	v_lshlrev_b64 v[222:223], 1, v[222:223]
	v_lshl_add_u64 v[222:223], s[50:51], 0, v[222:223]
	global_load_dwordx2 v[218:219], v[222:223], off
	v_or_b32_e32 v222, 0x70, v110
	v_mov_b32_e32 v223, v111
	v_lshlrev_b64 v[222:223], 1, v[222:223]
	v_lshl_add_u64 v[222:223], s[50:51], 0, v[222:223]
	global_load_dwordx2 v[220:221], v[222:223], off
	ds_bpermute_b32 v21, v70, v4
	v_xor_b32_e32 v14, 32, v238
	v_cmp_lt_i32_e32 vcc, v14, v20
	v_lshl_add_u64 v[16:17], s[52:53], 0, v[16:17]
	s_waitcnt lgkmcnt(0)
	v_add_f32_e32 v4, v4, v21
	v_cndmask_b32_e32 v14, v238, v14, vcc
	v_lshlrev_b32_e32 v71, 2, v14
	ds_bpermute_b32 v14, v71, v4
	s_waitcnt lgkmcnt(0)
	v_add_f32_e32 v4, v4, v14
	v_mul_f32_e32 v4, 0x3c000000, v4
	v_pk_add_f32 v[6:7], v[6:7], v[4:5] op_sel_hi:[1,0] neg_lo:[0,1] neg_hi:[0,1]
	v_pk_add_f32 v[8:9], v[8:9], v[4:5] op_sel_hi:[1,0] neg_lo:[0,1] neg_hi:[0,1]
	v_pk_mul_f32 v[32:33], v[6:7], v[6:7]
	v_pk_add_f32 v[14:15], v[0:1], v[4:5] op_sel_hi:[1,0] neg_lo:[0,1] neg_hi:[0,1]
	v_pk_add_f32 v[0:1], v[2:3], v[4:5] op_sel_hi:[1,0] neg_lo:[0,1] neg_hi:[0,1]
	v_pk_mul_f32 v[30:31], v[8:9], v[8:9]
	v_pk_add_f32 v[12:13], v[12:13], v[4:5] op_sel_hi:[1,0] neg_lo:[0,1] neg_hi:[0,1]
	v_pk_add_f32 v[10:11], v[10:11], v[4:5] op_sel_hi:[1,0] neg_lo:[0,1] neg_hi:[0,1]
	v_pk_add_f32 v[36:37], v[36:37], v[4:5] op_sel_hi:[1,0] neg_lo:[0,1] neg_hi:[0,1]
	v_pk_add_f32 v[34:35], v[34:35], v[4:5] op_sel_hi:[1,0] neg_lo:[0,1] neg_hi:[0,1]
	v_pk_add_f32 v[28:29], v[28:29], v[4:5] op_sel_hi:[1,0] neg_lo:[0,1] neg_hi:[0,1]
	v_pk_add_f32 v[26:27], v[26:27], v[4:5] op_sel_hi:[1,0] neg_lo:[0,1] neg_hi:[0,1]
	v_pk_add_f32 v[24:25], v[24:25], v[4:5] op_sel_hi:[1,0] neg_lo:[0,1] neg_hi:[0,1]
	v_pk_add_f32 v[22:23], v[22:23], v[4:5] op_sel_hi:[1,0] neg_lo:[0,1] neg_hi:[0,1]
	v_pk_add_f32 v[48:49], v[48:49], v[4:5] op_sel_hi:[1,0] neg_lo:[0,1] neg_hi:[0,1]
	v_pk_add_f32 v[46:47], v[46:47], v[4:5] op_sel_hi:[1,0] neg_lo:[0,1] neg_hi:[0,1]
	v_pk_add_f32 v[44:45], v[44:45], v[4:5] op_sel_hi:[1,0] neg_lo:[0,1] neg_hi:[0,1]
	v_pk_add_f32 v[42:43], v[42:43], v[4:5] op_sel_hi:[1,0] neg_lo:[0,1] neg_hi:[0,1]
	v_add_f32_e32 v4, v32, v33
	v_add_f32_e32 v4, v30, v4
	v_pk_mul_f32 v[40:41], v[10:11], v[10:11]
	v_add_f32_e32 v4, v31, v4
	v_add_f32_e32 v4, v40, v4
	v_pk_mul_f32 v[38:39], v[12:13], v[12:13]
	v_add_f32_e32 v4, v41, v4
	v_add_f32_e32 v4, v38, v4
	v_pk_mul_f32 v[52:53], v[34:35], v[34:35]
	v_add_f32_e32 v4, v39, v4
	v_add_f32_e32 v4, v52, v4
	v_pk_mul_f32 v[50:51], v[36:37], v[36:37]
	v_add_f32_e32 v4, v53, v4
	v_add_f32_e32 v4, v50, v4
	v_pk_mul_f32 v[56:57], v[26:27], v[26:27]
	v_add_f32_e32 v4, v51, v4
	v_add_f32_e32 v4, v56, v4
	v_pk_mul_f32 v[54:55], v[28:29], v[28:29]
	v_add_f32_e32 v4, v57, v4
	v_add_f32_e32 v4, v54, v4
	v_pk_mul_f32 v[60:61], v[22:23], v[22:23]
	v_add_f32_e32 v4, v55, v4
	v_add_f32_e32 v4, v60, v4
	v_pk_mul_f32 v[58:59], v[24:25], v[24:25]
	v_add_f32_e32 v4, v61, v4
	v_add_f32_e32 v4, v58, v4
	v_pk_mul_f32 v[64:65], v[46:47], v[46:47]
	v_add_f32_e32 v4, v59, v4
	v_add_f32_e32 v4, v64, v4
	v_pk_mul_f32 v[62:63], v[48:49], v[48:49]
	v_add_f32_e32 v4, v65, v4
	v_add_f32_e32 v4, v62, v4
	v_pk_mul_f32 v[68:69], v[42:43], v[42:43]
	v_add_f32_e32 v4, v63, v4
	v_add_f32_e32 v4, v68, v4
	v_pk_mul_f32 v[66:67], v[44:45], v[44:45]
	v_add_f32_e32 v4, v69, v4
	v_add_f32_e32 v4, v66, v4
	v_pk_mul_f32 v[20:21], v[14:15], v[14:15]
	v_add_f32_e32 v4, v67, v4
	v_add_f32_e32 v4, v20, v4
	v_pk_mul_f32 v[2:3], v[0:1], v[0:1]
	v_add_f32_e32 v4, v21, v4
	v_add_f32_e32 v2, v2, v4
	v_add_f32_e32 v4, v3, v2
	ds_bpermute_b32 v20, v70, v4
	s_waitcnt vmcnt(0)
	v_lshlrev_b32_e32 v2, 16, v18
	v_and_b32_e32 v3, 0xffff0000, v18
	v_lshlrev_b32_e32 v18, 16, v19
	v_and_b32_e32 v19, 0xffff0000, v19
	s_waitcnt lgkmcnt(0)
	v_add_f32_e32 v4, v4, v20
	ds_bpermute_b32 v21, v71, v4
	v_or_b32_e32 v20, 16, v110
	s_waitcnt lgkmcnt(0)
	v_add_f32_e32 v4, v4, v21
	v_fmamk_f32 v4, v4, 0x3c000000, v236
	v_mul_f32_e32 v21, 0x4b800000, v4
	v_cmp_gt_f32_e32 vcc, s0, v4
	s_nop 1
	v_cndmask_b32_e32 v4, v4, v21, vcc
	v_rsq_f32_e32 v4, v4
	v_mov_b32_e32 v21, v111
	v_lshlrev_b64 v[20:21], 1, v[20:21]
	v_lshl_add_u64 v[30:31], s[50:51], 0, v[20:21]
	v_mul_f32_e32 v32, 0x45800000, v4
	v_cndmask_b32_e32 v4, v4, v32, vcc
	v_pk_mul_f32 v[6:7], v[6:7], v[4:5] op_sel_hi:[1,0]
	v_pk_mul_f32 v[10:11], v[10:11], v[4:5] op_sel_hi:[1,0]
	v_pk_mul_f32 v[2:3], v[6:7], v[2:3]
	v_pk_mul_f32 v[6:7], v[8:9], v[4:5] op_sel_hi:[1,0]
	v_cvt_pk_bf16_f32 v2, v2, v3
	v_pk_mul_f32 v[6:7], v[6:7], v[18:19]
	v_pk_mul_f32 v[12:13], v[12:13], v[4:5] op_sel_hi:[1,0]
	v_cvt_pk_bf16_f32 v3, v6, v7
	global_store_dwordx2 v[16:17], v[2:3], off
	v_mov_b64_e32 v[2:3], v[208:209]
	v_mov_b32_e32 v7, v111
	v_or_b32_e32 v6, 32, v110
	v_lshlrev_b64 v[6:7], 1, v[6:7]
	v_lshl_add_u64 v[8:9], s[52:53], 0, v[20:21]
	v_lshl_add_u64 v[16:17], s[50:51], 0, v[6:7]
	v_lshl_add_u64 v[6:7], s[52:53], 0, v[6:7]
	v_pk_mul_f32 v[0:1], v[0:1], v[4:5] op_sel_hi:[1,0]
	v_lshlrev_b32_e32 v18, 16, v2
	v_and_b32_e32 v19, 0xffff0000, v2
	v_lshlrev_b32_e32 v2, 16, v3
	v_and_b32_e32 v3, 0xffff0000, v3
	v_pk_mul_f32 v[10:11], v[10:11], v[18:19]
	v_pk_mul_f32 v[2:3], v[12:13], v[2:3]
	v_cvt_pk_bf16_f32 v10, v10, v11
	v_cvt_pk_bf16_f32 v11, v2, v3
	global_store_dwordx2 v[8:9], v[10:11], off
	v_mov_b64_e32 v[2:3], v[210:211]
	v_pk_mul_f32 v[12:13], v[34:35], v[4:5] op_sel_hi:[1,0]
	v_pk_mul_f32 v[16:17], v[36:37], v[4:5] op_sel_hi:[1,0]
	v_mov_b32_e32 v9, v111
	v_or_b32_e32 v8, 48, v110
	v_lshlrev_b64 v[8:9], 1, v[8:9]
	v_lshl_add_u64 v[10:11], s[50:51], 0, v[8:9]
	v_lshl_add_u64 v[8:9], s[52:53], 0, v[8:9]
	v_lshlrev_b32_e32 v18, 16, v2
	v_and_b32_e32 v19, 0xffff0000, v2
	v_lshlrev_b32_e32 v2, 16, v3
	v_and_b32_e32 v3, 0xffff0000, v3
	v_pk_mul_f32 v[12:13], v[12:13], v[18:19]
	v_pk_mul_f32 v[2:3], v[16:17], v[2:3]
	v_cvt_pk_bf16_f32 v12, v12, v13
	v_cvt_pk_bf16_f32 v13, v2, v3
	global_store_dwordx2 v[6:7], v[12:13], off
	v_mov_b64_e32 v[2:3], v[212:213]
	v_pk_mul_f32 v[12:13], v[26:27], v[4:5] op_sel_hi:[1,0]
	v_pk_mul_f32 v[16:17], v[28:29], v[4:5] op_sel_hi:[1,0]
	v_mov_b32_e32 v7, v111
	v_or_b32_e32 v6, 64, v110
	v_lshlrev_b64 v[6:7], 1, v[6:7]
	v_lshl_add_u64 v[10:11], s[50:51], 0, v[6:7]
	v_lshl_add_u64 v[6:7], s[52:53], 0, v[6:7]
	v_lshlrev_b32_e32 v18, 16, v2
	v_and_b32_e32 v19, 0xffff0000, v2
	v_lshlrev_b32_e32 v2, 16, v3
	v_and_b32_e32 v3, 0xffff0000, v3
	v_pk_mul_f32 v[12:13], v[12:13], v[18:19]
	v_pk_mul_f32 v[2:3], v[16:17], v[2:3]
	v_cvt_pk_bf16_f32 v12, v12, v13
	v_cvt_pk_bf16_f32 v13, v2, v3
	global_store_dwordx2 v[8:9], v[12:13], off
	v_mov_b64_e32 v[2:3], v[214:215]
	v_pk_mul_f32 v[12:13], v[22:23], v[4:5] op_sel_hi:[1,0]
	v_pk_mul_f32 v[16:17], v[24:25], v[4:5] op_sel_hi:[1,0]
	v_mov_b32_e32 v9, v111
	v_or_b32_e32 v8, 0x50, v110
	v_lshlrev_b64 v[8:9], 1, v[8:9]
	v_lshl_add_u64 v[10:11], s[50:51], 0, v[8:9]
	v_lshl_add_u64 v[8:9], s[52:53], 0, v[8:9]
	v_lshlrev_b32_e32 v18, 16, v2
	v_and_b32_e32 v19, 0xffff0000, v2
	v_lshlrev_b32_e32 v2, 16, v3
	v_and_b32_e32 v3, 0xffff0000, v3
	v_pk_mul_f32 v[12:13], v[12:13], v[18:19]
	v_pk_mul_f32 v[2:3], v[16:17], v[2:3]
	v_cvt_pk_bf16_f32 v12, v12, v13
	v_cvt_pk_bf16_f32 v13, v2, v3
	global_store_dwordx2 v[6:7], v[12:13], off
	v_mov_b64_e32 v[2:3], v[216:217]
	v_pk_mul_f32 v[12:13], v[46:47], v[4:5] op_sel_hi:[1,0]
	v_pk_mul_f32 v[16:17], v[48:49], v[4:5] op_sel_hi:[1,0]
	v_mov_b32_e32 v7, v111
	v_or_b32_e32 v6, 0x60, v110
	v_lshlrev_b64 v[6:7], 1, v[6:7]
	v_lshl_add_u64 v[10:11], s[50:51], 0, v[6:7]
	v_or_b32_e32 v110, 0x70, v110
	v_lshl_add_u64 v[6:7], s[52:53], 0, v[6:7]
	v_lshlrev_b32_e32 v18, 16, v2
	v_and_b32_e32 v19, 0xffff0000, v2
	v_lshlrev_b32_e32 v2, 16, v3
	v_and_b32_e32 v3, 0xffff0000, v3
	v_pk_mul_f32 v[12:13], v[12:13], v[18:19]
	v_pk_mul_f32 v[2:3], v[16:17], v[2:3]
	v_cvt_pk_bf16_f32 v12, v12, v13
	v_cvt_pk_bf16_f32 v13, v2, v3
	global_store_dwordx2 v[8:9], v[12:13], off
	v_mov_b64_e32 v[2:3], v[218:219]
	v_pk_mul_f32 v[12:13], v[42:43], v[4:5] op_sel_hi:[1,0]
	v_pk_mul_f32 v[16:17], v[44:45], v[4:5] op_sel_hi:[1,0]
	v_lshlrev_b64 v[8:9], 1, v[110:111]
	v_lshl_add_u64 v[10:11], s[50:51], 0, v[8:9]
	v_lshlrev_b32_e32 v18, 16, v2
	v_and_b32_e32 v19, 0xffff0000, v2
	v_lshlrev_b32_e32 v2, 16, v3
	v_and_b32_e32 v3, 0xffff0000, v3
	v_pk_mul_f32 v[12:13], v[12:13], v[18:19]
	v_pk_mul_f32 v[2:3], v[16:17], v[2:3]
	v_cvt_pk_bf16_f32 v12, v12, v13
	v_cvt_pk_bf16_f32 v13, v2, v3
	global_store_dwordx2 v[6:7], v[12:13], off
	v_mov_b64_e32 v[2:3], v[220:221]
	v_pk_mul_f32 v[6:7], v[14:15], v[4:5] op_sel_hi:[1,0]
	v_lshlrev_b32_e32 v10, 16, v2
	v_and_b32_e32 v11, 0xffff0000, v2
	v_lshlrev_b32_e32 v2, 16, v3
	v_and_b32_e32 v3, 0xffff0000, v3
	v_pk_mul_f32 v[6:7], v[6:7], v[10:11]
	v_pk_mul_f32 v[0:1], v[0:1], v[2:3]
	v_cvt_pk_bf16_f32 v2, v6, v7
	v_cvt_pk_bf16_f32 v3, v0, v1
	v_lshl_add_u64 v[0:1], s[52:53], 0, v[8:9]
	global_store_dwordx2 v[0:1], v[2:3], off

.LBB0_3257:
	v_mov_b32_e32 v6, v74
	v_mov_b32_e32 v7, v78
	v_mov_b32_e32 v8, v75
	v_mov_b32_e32 v9, v79
	v_pk_add_f32 v[6:7], v[6:7], v[8:9]
	v_mov_b32_e32 v8, v76
	v_mov_b32_e32 v9, v80
	v_pk_add_f32 v[6:7], v[8:9], v[6:7]
	v_mov_b32_e32 v8, v77
	v_mov_b32_e32 v9, v81
	v_pk_add_f32 v[6:7], v[8:9], v[6:7]
	v_mov_b32_e32 v8, v71
	v_add_f32_e32 v4, 0, v6
	v_add_f32_e32 v4, v4, v7
	v_mov_b32_e32 v6, v70
	v_mov_b32_e32 v7, v66
	v_mov_b32_e32 v9, v67
	v_pk_add_f32 v[6:7], v[6:7], v[8:9]
	v_mov_b32_e32 v8, v72
	v_mov_b32_e32 v9, v68
	v_pk_add_f32 v[6:7], v[8:9], v[6:7]
	v_mov_b32_e32 v8, v73
	v_mov_b32_e32 v9, v69
	v_pk_add_f32 v[6:7], v[8:9], v[6:7]
	v_mov_b32_e32 v8, v63
	v_add_f32_e32 v4, v4, v6
	v_add_f32_e32 v4, v4, v7
	v_mov_b32_e32 v6, v62
	v_mov_b32_e32 v7, v58
	v_mov_b32_e32 v9, v59
	v_pk_add_f32 v[6:7], v[6:7], v[8:9]
	v_mov_b32_e32 v8, v64
	v_mov_b32_e32 v9, v60
	v_pk_add_f32 v[6:7], v[8:9], v[6:7]
	v_mov_b32_e32 v8, v65
	v_mov_b32_e32 v9, v61
	v_pk_add_f32 v[6:7], v[8:9], v[6:7]
	v_mov_b32_e32 v8, v55
	v_add_f32_e32 v4, v4, v6
	v_add_f32_e32 v4, v4, v7
	v_mov_b32_e32 v6, v54
	v_mov_b32_e32 v7, v0
	v_mov_b32_e32 v9, v1
	v_pk_add_f32 v[6:7], v[6:7], v[8:9]
	v_mov_b32_e32 v8, v56
	v_mov_b32_e32 v9, v2
	v_pk_add_f32 v[6:7], v[8:9], v[6:7]
	v_mov_b32_e32 v8, v57
	v_mov_b32_e32 v9, v3
	v_pk_add_f32 v[6:7], v[8:9], v[6:7]
	v_or3_b32 v110, v168, s9, v110
	v_add_f32_e32 v4, v4, v6
	v_add_f32_e32 v4, v4, v7
	v_and_b32_e32 v7, 64, v238
	v_xor_b32_e32 v6, 16, v238
	v_add_u32_e32 v12, 64, v7
	v_cmp_lt_i32_e32 vcc, v6, v12
	v_lshlrev_b64 v[8:9], 1, v[110:111]
	s_mov_b32 s0, 0x800000
	v_cndmask_b32_e32 v6, v238, v6, vcc
	v_lshlrev_b32_e32 v82, 2, v6
	v_lshl_add_u64 v[6:7], s[46:47], 0, v[8:9]
	global_load_dwordx2 v[10:11], v[6:7], off
	v_or_b32_e32 v222, 0x10, v110
	v_mov_b32_e32 v223, v111
	v_lshlrev_b64 v[222:223], 1, v[222:223]
	v_lshl_add_u64 v[222:223], s[46:47], 0, v[222:223]
	global_load_dwordx2 v[208:209], v[222:223], off
	v_or_b32_e32 v222, 0x20, v110
	v_mov_b32_e32 v223, v111
	v_lshlrev_b64 v[222:223], 1, v[222:223]
	v_lshl_add_u64 v[222:223], s[46:47], 0, v[222:223]
	global_load_dwordx2 v[210:211], v[222:223], off
	v_or_b32_e32 v222, 0x30, v110
	v_mov_b32_e32 v223, v111
	v_lshlrev_b64 v[222:223], 1, v[222:223]
	v_lshl_add_u64 v[222:223], s[46:47], 0, v[222:223]
	global_load_dwordx2 v[212:213], v[222:223], off
	v_or_b32_e32 v222, 0x40, v110
	v_mov_b32_e32 v223, v111
	v_lshlrev_b64 v[222:223], 1, v[222:223]
	v_lshl_add_u64 v[222:223], s[46:47], 0, v[222:223]
	global_load_dwordx2 v[214:215], v[222:223], off
	v_or_b32_e32 v222, 0x50, v110
	v_mov_b32_e32 v223, v111
	v_lshlrev_b64 v[222:223], 1, v[222:223]
	v_lshl_add_u64 v[222:223], s[46:47], 0, v[222:223]
	global_load_dwordx2 v[216:217], v[222:223], off
	v_or_b32_e32 v222, 0x60, v110
	v_mov_b32_e32 v223, v111
	v_lshlrev_b64 v[222:223], 1, v[222:223]
	v_lshl_add_u64 v[222:223], s[46:47], 0, v[222:223]
	global_load_dwordx2 v[218:219], v[222:223], off
	v_or_b32_e32 v222, 0x70, v110
	v_mov_b32_e32 v223, v111
	v_lshlrev_b64 v[222:223], 1, v[222:223]
	v_lshl_add_u64 v[222:223], s[46:47], 0, v[222:223]
	global_load_dwordx2 v[220:221], v[222:223], off
	ds_bpermute_b32 v13, v82, v4
	v_xor_b32_e32 v6, 32, v238
	v_cmp_lt_i32_e32 vcc, v6, v12
	v_lshl_add_u64 v[8:9], s[48:49], 0, v[8:9]
	s_waitcnt lgkmcnt(0)
	v_add_f32_e32 v4, v4, v13
	v_cndmask_b32_e32 v6, v238, v6, vcc
	v_lshlrev_b32_e32 v83, 2, v6
	ds_bpermute_b32 v6, v83, v4
	s_waitcnt lgkmcnt(0)
	v_add_f32_e32 v4, v4, v6
	v_mul_f32_e32 v4, 0x3c000000, v4
	v_pk_add_f32 v[18:19], v[74:75], v[4:5] op_sel_hi:[1,0] neg_lo:[0,1] neg_hi:[0,1]
	v_pk_add_f32 v[14:15], v[76:77], v[4:5] op_sel_hi:[1,0] neg_lo:[0,1] neg_hi:[0,1]
	v_pk_mul_f32 v[20:21], v[18:19], v[18:19]
	v_pk_add_f32 v[6:7], v[0:1], v[4:5] op_sel_hi:[1,0] neg_lo:[0,1] neg_hi:[0,1]
	v_pk_add_f32 v[0:1], v[2:3], v[4:5] op_sel_hi:[1,0] neg_lo:[0,1] neg_hi:[0,1]
	v_pk_mul_f32 v[16:17], v[14:15], v[14:15]
	s_waitcnt vmcnt(8)
	v_pk_add_f32 v[22:23], v[80:81], v[4:5] op_sel_hi:[1,0] neg_lo:[0,1] neg_hi:[0,1]
	s_waitcnt vmcnt(7)
	v_pk_add_f32 v[26:27], v[78:79], v[4:5] op_sel_hi:[1,0] neg_lo:[0,1] neg_hi:[0,1]
	s_waitcnt vmcnt(6)
	v_pk_add_f32 v[30:31], v[72:73], v[4:5] op_sel_hi:[1,0] neg_lo:[0,1] neg_hi:[0,1]
	s_waitcnt vmcnt(5)
	v_pk_add_f32 v[34:35], v[70:71], v[4:5] op_sel_hi:[1,0] neg_lo:[0,1] neg_hi:[0,1]
	s_waitcnt vmcnt(4)
	v_pk_add_f32 v[38:39], v[68:69], v[4:5] op_sel_hi:[1,0] neg_lo:[0,1] neg_hi:[0,1]
	s_waitcnt vmcnt(3)
	v_pk_add_f32 v[42:43], v[66:67], v[4:5] op_sel_hi:[1,0] neg_lo:[0,1] neg_hi:[0,1]
	s_waitcnt vmcnt(2)
	v_pk_add_f32 v[46:47], v[64:65], v[4:5] op_sel_hi:[1,0] neg_lo:[0,1] neg_hi:[0,1]
	s_waitcnt vmcnt(1)
	v_pk_add_f32 v[50:51], v[62:63], v[4:5] op_sel_hi:[1,0] neg_lo:[0,1] neg_hi:[0,1]
	v_pk_add_f32 v[60:61], v[60:61], v[4:5] op_sel_hi:[1,0] neg_lo:[0,1] neg_hi:[0,1]
	v_pk_add_f32 v[58:59], v[58:59], v[4:5] op_sel_hi:[1,0] neg_lo:[0,1] neg_hi:[0,1]
	v_pk_add_f32 v[56:57], v[56:57], v[4:5] op_sel_hi:[1,0] neg_lo:[0,1] neg_hi:[0,1]
	v_pk_add_f32 v[54:55], v[54:55], v[4:5] op_sel_hi:[1,0] neg_lo:[0,1] neg_hi:[0,1]
	v_add_f32_e32 v4, v20, v21
	v_add_f32_e32 v4, v16, v4
	v_pk_mul_f32 v[28:29], v[26:27], v[26:27]
	v_add_f32_e32 v4, v17, v4
	v_add_f32_e32 v4, v28, v4
	v_pk_mul_f32 v[24:25], v[22:23], v[22:23]
	v_add_f32_e32 v4, v29, v4
	v_add_f32_e32 v4, v24, v4
	v_pk_mul_f32 v[36:37], v[34:35], v[34:35]
	v_add_f32_e32 v4, v25, v4
	v_add_f32_e32 v4, v36, v4
	v_pk_mul_f32 v[32:33], v[30:31], v[30:31]
	v_add_f32_e32 v4, v37, v4
	v_add_f32_e32 v4, v32, v4
	v_pk_mul_f32 v[44:45], v[42:43], v[42:43]
	v_add_f32_e32 v4, v33, v4
	v_add_f32_e32 v4, v44, v4
	v_pk_mul_f32 v[40:41], v[38:39], v[38:39]
	v_add_f32_e32 v4, v45, v4
	v_add_f32_e32 v4, v40, v4
	v_pk_mul_f32 v[52:53], v[50:51], v[50:51]
	v_add_f32_e32 v4, v41, v4
	v_add_f32_e32 v4, v52, v4
	v_pk_mul_f32 v[48:49], v[46:47], v[46:47]
	v_add_f32_e32 v4, v53, v4
	v_add_f32_e32 v4, v48, v4
	v_pk_mul_f32 v[64:65], v[58:59], v[58:59]
	v_add_f32_e32 v4, v49, v4
	v_add_f32_e32 v4, v64, v4
	v_pk_mul_f32 v[62:63], v[60:61], v[60:61]
	v_add_f32_e32 v4, v65, v4
	v_add_f32_e32 v4, v62, v4
	v_pk_mul_f32 v[68:69], v[54:55], v[54:55]
	v_add_f32_e32 v4, v63, v4
	v_add_f32_e32 v4, v68, v4
	v_pk_mul_f32 v[66:67], v[56:57], v[56:57]
	v_add_f32_e32 v4, v69, v4
	v_add_f32_e32 v4, v66, v4
	v_pk_mul_f32 v[12:13], v[6:7], v[6:7]
	v_add_f32_e32 v4, v67, v4
	v_add_f32_e32 v4, v12, v4
	v_pk_mul_f32 v[2:3], v[0:1], v[0:1]
	v_add_f32_e32 v4, v13, v4
	v_add_f32_e32 v2, v2, v4
	v_add_f32_e32 v4, v3, v2
	ds_bpermute_b32 v12, v82, v4
	s_waitcnt vmcnt(0)
	v_lshlrev_b32_e32 v2, 16, v10
	v_and_b32_e32 v3, 0xffff0000, v10
	v_lshlrev_b32_e32 v10, 16, v11
	v_and_b32_e32 v11, 0xffff0000, v11
	s_waitcnt lgkmcnt(0)
	v_add_f32_e32 v4, v4, v12
	ds_bpermute_b32 v13, v83, v4
	v_or_b32_e32 v12, 16, v110
	s_waitcnt lgkmcnt(0)
	v_add_f32_e32 v4, v4, v13
	v_fmamk_f32 v4, v4, 0x3c000000, v236
	v_mul_f32_e32 v13, 0x4b800000, v4
	v_cmp_gt_f32_e32 vcc, s0, v4
	s_nop 1
	v_cndmask_b32_e32 v4, v4, v13, vcc
	v_rsq_f32_e32 v4, v4
	v_mov_b32_e32 v13, v111
	v_lshlrev_b64 v[12:13], 1, v[12:13]
	v_lshl_add_u64 v[16:17], s[46:47], 0, v[12:13]
	v_mul_f32_e32 v20, 0x45800000, v4
	v_cndmask_b32_e32 v4, v4, v20, vcc
	v_pk_mul_f32 v[18:19], v[18:19], v[4:5] op_sel_hi:[1,0]
	v_pk_mul_f32 v[14:15], v[14:15], v[4:5] op_sel_hi:[1,0]
	v_pk_mul_f32 v[2:3], v[18:19], v[2:3]
	v_pk_mul_f32 v[10:11], v[14:15], v[10:11]
	v_cvt_pk_bf16_f32 v2, v2, v3
	v_cvt_pk_bf16_f32 v3, v10, v11
	global_store_dwordx2 v[8:9], v[2:3], off
	v_mov_b64_e32 v[2:3], v[208:209]
	v_pk_mul_f32 v[16:17], v[26:27], v[4:5] op_sel_hi:[1,0]
	v_mov_b32_e32 v9, v111
	v_or_b32_e32 v8, 32, v110
	v_lshlrev_b64 v[8:9], 1, v[8:9]
	v_lshl_add_u64 v[10:11], s[48:49], 0, v[12:13]
	v_lshl_add_u64 v[12:13], s[46:47], 0, v[8:9]
	v_lshl_add_u64 v[8:9], s[48:49], 0, v[8:9]
	v_pk_mul_f32 v[6:7], v[6:7], v[4:5] op_sel_hi:[1,0]
	v_pk_mul_f32 v[0:1], v[0:1], v[4:5] op_sel_hi:[1,0]
	v_lshlrev_b32_e32 v14, 16, v2
	v_and_b32_e32 v15, 0xffff0000, v2
	v_pk_mul_f32 v[14:15], v[16:17], v[14:15]
	v_lshlrev_b32_e32 v2, 16, v3
	v_pk_mul_f32 v[16:17], v[22:23], v[4:5] op_sel_hi:[1,0]
	v_and_b32_e32 v3, 0xffff0000, v3
	v_pk_mul_f32 v[2:3], v[16:17], v[2:3]
	v_cvt_pk_bf16_f32 v14, v14, v15
	v_cvt_pk_bf16_f32 v15, v2, v3
	global_store_dwordx2 v[10:11], v[14:15], off
	v_mov_b64_e32 v[2:3], v[210:211]
	v_pk_mul_f32 v[14:15], v[34:35], v[4:5] op_sel_hi:[1,0]
	v_pk_mul_f32 v[16:17], v[30:31], v[4:5] op_sel_hi:[1,0]
	v_mov_b32_e32 v11, v111
	v_or_b32_e32 v10, 48, v110
	v_lshlrev_b64 v[10:11], 1, v[10:11]
	v_lshl_add_u64 v[12:13], s[46:47], 0, v[10:11]
	v_lshl_add_u64 v[10:11], s[48:49], 0, v[10:11]
	v_lshlrev_b32_e32 v18, 16, v2
	v_and_b32_e32 v19, 0xffff0000, v2
	v_lshlrev_b32_e32 v2, 16, v3
	v_and_b32_e32 v3, 0xffff0000, v3
	v_pk_mul_f32 v[14:15], v[14:15], v[18:19]
	v_pk_mul_f32 v[2:3], v[16:17], v[2:3]
	v_cvt_pk_bf16_f32 v14, v14, v15
	v_cvt_pk_bf16_f32 v15, v2, v3
	global_store_dwordx2 v[8:9], v[14:15], off
	v_mov_b64_e32 v[2:3], v[212:213]
	v_pk_mul_f32 v[14:15], v[42:43], v[4:5] op_sel_hi:[1,0]
	v_pk_mul_f32 v[16:17], v[38:39], v[4:5] op_sel_hi:[1,0]
	v_mov_b32_e32 v9, v111
	v_or_b32_e32 v8, 64, v110
	v_lshlrev_b64 v[8:9], 1, v[8:9]
	v_lshl_add_u64 v[12:13], s[46:47], 0, v[8:9]
	v_lshl_add_u64 v[8:9], s[48:49], 0, v[8:9]
	v_lshlrev_b32_e32 v18, 16, v2
	v_and_b32_e32 v19, 0xffff0000, v2
	v_lshlrev_b32_e32 v2, 16, v3
	v_and_b32_e32 v3, 0xffff0000, v3
	v_pk_mul_f32 v[14:15], v[14:15], v[18:19]
	v_pk_mul_f32 v[2:3], v[16:17], v[2:3]
	v_cvt_pk_bf16_f32 v14, v14, v15
	v_cvt_pk_bf16_f32 v15, v2, v3
	global_store_dwordx2 v[10:11], v[14:15], off
	v_mov_b64_e32 v[2:3], v[214:215]
	v_pk_mul_f32 v[14:15], v[50:51], v[4:5] op_sel_hi:[1,0]
	v_pk_mul_f32 v[16:17], v[46:47], v[4:5] op_sel_hi:[1,0]
	v_mov_b32_e32 v11, v111
	v_or_b32_e32 v10, 0x50, v110
	v_lshlrev_b64 v[10:11], 1, v[10:11]
	v_lshl_add_u64 v[12:13], s[46:47], 0, v[10:11]
	v_lshl_add_u64 v[10:11], s[48:49], 0, v[10:11]
	v_lshlrev_b32_e32 v18, 16, v2
	v_and_b32_e32 v19, 0xffff0000, v2
	v_lshlrev_b32_e32 v2, 16, v3
	v_and_b32_e32 v3, 0xffff0000, v3
	v_pk_mul_f32 v[14:15], v[14:15], v[18:19]
	v_pk_mul_f32 v[2:3], v[16:17], v[2:3]
	v_cvt_pk_bf16_f32 v14, v14, v15
	v_cvt_pk_bf16_f32 v15, v2, v3
	global_store_dwordx2 v[8:9], v[14:15], off
	v_mov_b64_e32 v[2:3], v[216:217]
	v_pk_mul_f32 v[14:15], v[58:59], v[4:5] op_sel_hi:[1,0]
	v_pk_mul_f32 v[16:17], v[60:61], v[4:5] op_sel_hi:[1,0]
	v_mov_b32_e32 v9, v111
	v_or_b32_e32 v8, 0x60, v110
	v_lshlrev_b64 v[8:9], 1, v[8:9]
	v_lshl_add_u64 v[12:13], s[46:47], 0, v[8:9]
	v_or_b32_e32 v110, 0x70, v110
	v_lshl_add_u64 v[8:9], s[48:49], 0, v[8:9]
	v_lshlrev_b32_e32 v18, 16, v2
	v_and_b32_e32 v19, 0xffff0000, v2
	v_lshlrev_b32_e32 v2, 16, v3
	v_and_b32_e32 v3, 0xffff0000, v3
	v_pk_mul_f32 v[14:15], v[14:15], v[18:19]
	v_pk_mul_f32 v[2:3], v[16:17], v[2:3]
	v_cvt_pk_bf16_f32 v14, v14, v15
	v_cvt_pk_bf16_f32 v15, v2, v3
	global_store_dwordx2 v[10:11], v[14:15], off
	v_mov_b64_e32 v[2:3], v[218:219]
	v_pk_mul_f32 v[14:15], v[54:55], v[4:5] op_sel_hi:[1,0]
	v_pk_mul_f32 v[16:17], v[56:57], v[4:5] op_sel_hi:[1,0]
	v_lshlrev_b64 v[10:11], 1, v[110:111]
	v_lshl_add_u64 v[12:13], s[46:47], 0, v[10:11]
	v_lshlrev_b32_e32 v18, 16, v2
	v_and_b32_e32 v19, 0xffff0000, v2
	v_lshlrev_b32_e32 v2, 16, v3
	v_and_b32_e32 v3, 0xffff0000, v3
	v_pk_mul_f32 v[14:15], v[14:15], v[18:19]
	v_pk_mul_f32 v[2:3], v[16:17], v[2:3]
	v_cvt_pk_bf16_f32 v14, v14, v15
	v_cvt_pk_bf16_f32 v15, v2, v3
	global_store_dwordx2 v[8:9], v[14:15], off
	v_mov_b64_e32 v[2:3], v[220:221]
	v_lshlrev_b32_e32 v8, 16, v2
	v_and_b32_e32 v9, 0xffff0000, v2
	v_lshlrev_b32_e32 v2, 16, v3
	v_and_b32_e32 v3, 0xffff0000, v3
	v_pk_mul_f32 v[6:7], v[6:7], v[8:9]
	v_pk_mul_f32 v[0:1], v[0:1], v[2:3]
	v_cvt_pk_bf16_f32 v2, v6, v7
	v_cvt_pk_bf16_f32 v3, v0, v1
	v_lshl_add_u64 v[0:1], s[48:49], 0, v[10:11]
	global_store_dwordx2 v[0:1], v[2:3], off

.LBB0_3542:
	s_or_b32 s5, s5, s4
	s_lshl_b32 s5, s5, 2
	s_or_b32 s94, s5, s2
	v_cndmask_b32_e64 v100, v98, v99, s[0:1]
	s_lshl_b64 s[8:9], s[94:95], 15
	v_lshl_add_u64 v[96:97], v[50:51], 0, s[8:9]
	v_pk_mul_f32 v[14:15], v[100:101], v[52:53] op_sel_hi:[0,1]
	v_pk_mul_f32 v[16:17], v[100:101], v[38:39] op_sel_hi:[0,1]
	v_cvt_pk_bf16_f32 v14, v14, v15
	v_cvt_pk_bf16_f32 v15, v16, v17
	v_pk_mul_f32 v[16:17], v[100:101], v[54:55] op_sel_hi:[0,1]
	v_pk_mul_f32 v[18:19], v[100:101], v[40:41] op_sel_hi:[0,1]
	v_lshl_add_u64 v[94:95], v[96:97], 0, v[4:5]
	v_cvt_pk_bf16_f32 v16, v16, v17
	v_cvt_pk_bf16_f32 v17, v18, v19
	global_load_dwordx4 v[144:147], v[94:95], off
	v_lshl_add_u64 v[178:179], v[96:97], 0, v[56:57]
	global_load_dwordx4 v[148:151], v[178:179], off
	v_lshl_add_u64 v[180:181], v[96:97], 0, v[66:67]
	global_load_dwordx4 v[152:155], v[180:181], off
	v_lshl_add_u64 v[182:183], v[96:97], 0, v[58:59]
	global_load_dwordx4 v[156:159], v[182:183], off
	v_lshl_add_u64 v[184:185], v[96:97], 0, v[68:69]
	global_load_dwordx4 v[160:163], v[184:185], off
	v_lshl_add_u64 v[186:187], v[96:97], 0, v[60:61]
	global_load_dwordx4 v[164:167], v[186:187], off
	v_lshl_add_u64 v[188:189], v[96:97], 0, v[62:63]
	global_load_dwordx4 v[168:171], v[188:189], off
	v_lshl_add_u64 v[190:191], v[96:97], 0, v[64:65]
	global_load_dwordx4 v[172:175], v[190:191], off
	v_lshl_add_u64 v[102:103], v[96:97], 0, 64
	s_mov_b64 s[8:9], 0xc0
	s_mov_b32 s5, 1
	s_and_b64 vcc, exec, s[0:1]
	s_mov_b64 s[0:1], 0
	s_waitcnt vmcnt(7)
	v_mfma_f32_16x16x32_bf16 v[6:9], v[144:147], v[14:17], v[6:9]
	s_nop 0
	s_waitcnt vmcnt(6)
	v_mfma_f32_16x16x32_bf16 v[10:13], v[148:151], v[14:17], v[10:13]
	s_waitcnt vmcnt(5)
	v_mfma_f32_16x16x32_bf16 v[34:37], v[152:155], v[14:17], v[42:45]
	s_nop 2
	s_waitcnt vmcnt(4)
	v_mfma_f32_16x16x32_bf16 v[18:21], v[156:159], v[14:17], v[30:33]
	s_nop 2
	s_waitcnt vmcnt(3)
	v_mfma_f32_16x16x32_bf16 v[0:3], v[160:163], v[14:17], v[0:3]
	v_mul_f32_e64 v42, v100, v76
	v_mul_f32_e64 v43, v100, v77
	s_waitcnt vmcnt(2)
	v_mfma_f32_16x16x32_bf16 v[26:29], v[164:167], v[14:17], v[26:29]
	s_waitcnt vmcnt(1)
	v_mfma_f32_16x16x32_bf16 v[22:25], v[168:171], v[14:17], v[22:25]
	s_waitcnt vmcnt(0)
	v_mfma_f32_16x16x32_bf16 v[30:33], v[172:175], v[14:17], v[46:49]
	v_mul_f32_e64 v14, v100, v70
	v_mul_f32_e64 v15, v100, v71
	v_pk_mul_f32 v[16:17], v[100:101], v[72:73] op_sel_hi:[0,1]
	v_cvt_pk_bf16_f32 v14, v14, v15
	v_cvt_pk_bf16_f32 v15, v16, v17
	v_pk_mul_f32 v[16:17], v[100:101], v[74:75] op_sel_hi:[0,1]
	v_cvt_pk_bf16_f32 v16, v16, v17
	v_cvt_pk_bf16_f32 v17, v42, v43
	global_load_dwordx4 v[144:147], v[94:95], off offset:64
	v_lshl_add_u64 v[178:179], v[102:103], 0, v[56:57]
	global_load_dwordx4 v[148:151], v[178:179], off
	v_lshl_add_u64 v[180:181], v[102:103], 0, v[58:59]
	global_load_dwordx4 v[152:155], v[180:181], off
	v_lshl_add_u64 v[182:183], v[102:103], 0, v[60:61]
	global_load_dwordx4 v[156:159], v[182:183], off
	v_lshl_add_u64 v[184:185], v[102:103], 0, v[62:63]
	global_load_dwordx4 v[160:163], v[184:185], off
	v_lshl_add_u64 v[186:187], v[102:103], 0, v[64:65]
	global_load_dwordx4 v[164:167], v[186:187], off
	v_lshl_add_u64 v[188:189], v[102:103], 0, v[66:67]
	global_load_dwordx4 v[168:171], v[188:189], off
	v_lshl_add_u64 v[190:191], v[102:103], 0, v[68:69]
	global_load_dwordx4 v[172:175], v[190:191], off
	s_waitcnt vmcnt(7)
	v_mfma_f32_16x16x32_bf16 v[6:9], v[144:147], v[14:17], v[6:9]
	s_waitcnt vmcnt(6)
	v_mfma_f32_16x16x32_bf16 v[10:13], v[148:151], v[14:17], v[10:13]
	s_waitcnt vmcnt(5)
	v_mfma_f32_16x16x32_bf16 v[18:21], v[152:155], v[14:17], v[18:21]
	s_waitcnt vmcnt(4)
	v_mfma_f32_16x16x32_bf16 v[26:29], v[156:159], v[14:17], v[26:29]
	s_waitcnt vmcnt(3)
	v_mfma_f32_16x16x32_bf16 v[22:25], v[160:163], v[14:17], v[22:25]
	s_waitcnt vmcnt(2)
	v_mfma_f32_16x16x32_bf16 v[42:45], v[164:167], v[14:17], v[30:33]
	s_nop 2
	s_waitcnt vmcnt(1)
	v_mfma_f32_16x16x32_bf16 v[46:49], v[168:171], v[14:17], v[34:37]
	v_lshl_add_u64 v[102:103], v[96:97], 0, s[38:39]
	v_lshl_add_u64 v[96:97], v[96:97], 0, s[8:9]
	s_waitcnt vmcnt(0)
	v_mfma_f32_16x16x32_bf16 v[0:3], v[172:175], v[14:17], v[0:3]
	v_mul_f32_e64 v14, v100, v78
	v_mul_f32_e64 v15, v100, v79
	v_pk_mul_f32 v[16:17], v[100:101], v[80:81] op_sel_hi:[0,1]
	v_cvt_pk_bf16_f32 v14, v14, v15
	v_cvt_pk_bf16_f32 v15, v16, v17
	v_pk_mul_f32 v[16:17], v[100:101], v[82:83] op_sel_hi:[0,1]
	v_pk_mul_f32 v[30:31], v[100:101], v[84:85] op_sel_hi:[0,1]
	v_cvt_pk_bf16_f32 v16, v16, v17
	v_cvt_pk_bf16_f32 v17, v30, v31
	global_load_dwordx4 v[144:147], v[94:95], off offset:128
	v_lshl_add_u64 v[178:179], v[102:103], 0, v[56:57]
	global_load_dwordx4 v[148:151], v[178:179], off
	v_lshl_add_u64 v[180:181], v[102:103], 0, v[58:59]
	global_load_dwordx4 v[152:155], v[180:181], off
	v_lshl_add_u64 v[182:183], v[102:103], 0, v[60:61]
	global_load_dwordx4 v[156:159], v[182:183], off
	v_lshl_add_u64 v[184:185], v[102:103], 0, v[62:63]
	global_load_dwordx4 v[160:163], v[184:185], off
	v_lshl_add_u64 v[186:187], v[102:103], 0, v[64:65]
	global_load_dwordx4 v[164:167], v[186:187], off
	v_lshl_add_u64 v[188:189], v[102:103], 0, v[66:67]
	global_load_dwordx4 v[168:171], v[188:189], off
	v_lshl_add_u64 v[190:191], v[102:103], 0, v[68:69]
	global_load_dwordx4 v[172:175], v[190:191], off
	s_waitcnt vmcnt(7)
	v_mfma_f32_16x16x32_bf16 v[6:9], v[144:147], v[14:17], v[6:9]
	s_waitcnt vmcnt(6)
	v_mfma_f32_16x16x32_bf16 v[10:13], v[148:151], v[14:17], v[10:13]
	s_waitcnt vmcnt(5)
	v_mfma_f32_16x16x32_bf16 v[30:33], v[152:155], v[14:17], v[18:21]
	s_nop 2
	s_waitcnt vmcnt(4)
	v_mfma_f32_16x16x32_bf16 v[26:29], v[156:159], v[14:17], v[26:29]
	s_waitcnt vmcnt(3)
	v_mfma_f32_16x16x32_bf16 v[22:25], v[160:163], v[14:17], v[22:25]
	s_waitcnt vmcnt(2)
	v_mfma_f32_16x16x32_bf16 v[34:37], v[164:167], v[14:17], v[42:45]
	s_nop 1
	s_nop 0
	s_waitcnt vmcnt(1)
	v_mfma_f32_16x16x32_bf16 v[18:21], v[168:171], v[14:17], v[46:49]
	s_waitcnt vmcnt(0)
	v_mfma_f32_16x16x32_bf16 v[0:3], v[172:175], v[14:17], v[0:3]
	v_mul_f32_e64 v14, v100, v86
	v_mul_f32_e64 v15, v100, v87
	v_pk_mul_f32 v[16:17], v[100:101], v[88:89] op_sel_hi:[0,1]
	v_cvt_pk_bf16_f32 v14, v14, v15
	v_cvt_pk_bf16_f32 v15, v16, v17
	v_pk_mul_f32 v[16:17], v[100:101], v[90:91] op_sel_hi:[0,1]
	v_pk_mul_f32 v[42:43], v[100:101], v[92:93] op_sel_hi:[0,1]
	v_cvt_pk_bf16_f32 v16, v16, v17
	v_cvt_pk_bf16_f32 v17, v42, v43
	global_load_dwordx4 v[144:147], v[94:95], off offset:192
	v_lshl_add_u64 v[178:179], v[96:97], 0, v[56:57]
	global_load_dwordx4 v[148:151], v[178:179], off
	v_lshl_add_u64 v[180:181], v[96:97], 0, v[58:59]
	global_load_dwordx4 v[152:155], v[180:181], off
	v_lshl_add_u64 v[182:183], v[96:97], 0, v[60:61]
	global_load_dwordx4 v[156:159], v[182:183], off
	v_lshl_add_u64 v[184:185], v[96:97], 0, v[62:63]
	global_load_dwordx4 v[160:163], v[184:185], off
	v_lshl_add_u64 v[186:187], v[96:97], 0, v[64:65]
	global_load_dwordx4 v[164:167], v[186:187], off
	v_lshl_add_u64 v[188:189], v[96:97], 0, v[66:67]
	global_load_dwordx4 v[168:171], v[188:189], off
	v_lshl_add_u64 v[190:191], v[96:97], 0, v[68:69]
	global_load_dwordx4 v[172:175], v[190:191], off
	s_waitcnt vmcnt(7)
	v_mfma_f32_16x16x32_bf16 v[6:9], v[144:147], v[14:17], v[6:9]
	s_waitcnt vmcnt(6)
	v_mfma_f32_16x16x32_bf16 v[10:13], v[148:151], v[14:17], v[10:13]
	s_waitcnt vmcnt(5)
	v_mfma_f32_16x16x32_bf16 v[30:33], v[152:155], v[14:17], v[30:33]
	s_waitcnt vmcnt(4)
	v_mfma_f32_16x16x32_bf16 v[26:29], v[156:159], v[14:17], v[26:29]
	s_waitcnt vmcnt(3)
	v_mfma_f32_16x16x32_bf16 v[22:25], v[160:163], v[14:17], v[22:25]
	s_waitcnt vmcnt(2)
	v_mfma_f32_16x16x32_bf16 v[46:49], v[164:167], v[14:17], v[34:37]
	s_nop 2
	s_waitcnt vmcnt(1)
	v_mfma_f32_16x16x32_bf16 v[42:45], v[168:171], v[14:17], v[18:21]
	s_nop 2
	s_waitcnt vmcnt(0)
	v_mfma_f32_16x16x32_bf16 v[0:3], v[172:175], v[14:17], v[0:3]
	s_cbranch_vccnz .LBB0_3542
	v_mov_b32_e32 v14, v6
	v_mov_b32_e32 v15, v10
	v_mov_b32_e32 v16, v7
	v_mov_b32_e32 v17, v11
	v_pk_add_f32 v[14:15], v[14:15], v[16:17]
	v_mov_b32_e32 v16, v8
	v_mov_b32_e32 v17, v12
	v_pk_add_f32 v[14:15], v[16:17], v[14:15]
	v_mov_b32_e32 v16, v9
	v_mov_b32_e32 v17, v13
	v_pk_add_f32 v[14:15], v[16:17], v[14:15]
	v_mov_b32_e32 v16, v31
	v_add_f32_e32 v4, 0, v14
	v_add_f32_e32 v4, v4, v15
	v_mov_b32_e32 v14, v30
	v_mov_b32_e32 v15, v26
	v_mov_b32_e32 v17, v27
	v_pk_add_f32 v[14:15], v[14:15], v[16:17]
	v_mov_b32_e32 v16, v32
	v_mov_b32_e32 v17, v28
	v_pk_add_f32 v[14:15], v[16:17], v[14:15]
	v_mov_b32_e32 v16, v33
	v_mov_b32_e32 v17, v29
	v_pk_add_f32 v[14:15], v[16:17], v[14:15]
	v_mov_b32_e32 v16, v23
	v_add_f32_e32 v4, v4, v14
	v_add_f32_e32 v4, v4, v15
	v_mov_b32_e32 v14, v22
	v_mov_b32_e32 v15, v46
	v_mov_b32_e32 v17, v47
	v_pk_add_f32 v[14:15], v[14:15], v[16:17]
	v_mov_b32_e32 v16, v24
	v_mov_b32_e32 v17, v48
	v_pk_add_f32 v[14:15], v[16:17], v[14:15]
	v_mov_b32_e32 v16, v25
	v_mov_b32_e32 v17, v49
	v_pk_add_f32 v[14:15], v[16:17], v[14:15]
	v_mov_b32_e32 v16, v43
	v_add_f32_e32 v4, v4, v14
	v_add_f32_e32 v4, v4, v15
	v_mov_b32_e32 v14, v42
	v_mov_b32_e32 v15, v0
	v_mov_b32_e32 v17, v1
	v_pk_add_f32 v[14:15], v[14:15], v[16:17]
	v_mov_b32_e32 v16, v44
	v_mov_b32_e32 v17, v2
	v_pk_add_f32 v[14:15], v[16:17], v[14:15]
	v_mov_b32_e32 v16, v45
	v_mov_b32_e32 v17, v3
	v_pk_add_f32 v[14:15], v[16:17], v[14:15]
	v_or3_b32 v110, v141, s6, v110
	v_add_f32_e32 v4, v4, v14
	v_add_f32_e32 v4, v4, v15
	v_and_b32_e32 v15, 64, v238
	v_xor_b32_e32 v14, 16, v238
	v_add_u32_e32 v20, 64, v15
	v_cmp_lt_i32_e32 vcc, v14, v20
	v_lshlrev_b64 v[16:17], 1, v[110:111]
	s_mov_b32 s0, 0x800000
	v_cndmask_b32_e32 v14, v238, v14, vcc
	v_lshlrev_b32_e32 v70, 2, v14
	v_lshl_add_u64 v[14:15], s[46:47], 0, v[16:17]
	global_load_dwordx2 v[18:19], v[14:15], off
	v_or_b32_e32 v222, 0x10, v110
	v_mov_b32_e32 v223, v111
	v_lshlrev_b64 v[222:223], 1, v[222:223]
	v_lshl_add_u64 v[222:223], s[46:47], 0, v[222:223]
	global_load_dwordx2 v[208:209], v[222:223], off
	v_or_b32_e32 v222, 0x20, v110
	v_mov_b32_e32 v223, v111
	v_lshlrev_b64 v[222:223], 1, v[222:223]
	v_lshl_add_u64 v[222:223], s[46:47], 0, v[222:223]
	global_load_dwordx2 v[210:211], v[222:223], off
	v_or_b32_e32 v222, 0x30, v110
	v_mov_b32_e32 v223, v111
	v_lshlrev_b64 v[222:223], 1, v[222:223]
	v_lshl_add_u64 v[222:223], s[46:47], 0, v[222:223]
	global_load_dwordx2 v[212:213], v[222:223], off
	v_or_b32_e32 v222, 0x40, v110
	v_mov_b32_e32 v223, v111
	v_lshlrev_b64 v[222:223], 1, v[222:223]
	v_lshl_add_u64 v[222:223], s[46:47], 0, v[222:223]
	global_load_dwordx2 v[214:215], v[222:223], off
	v_or_b32_e32 v222, 0x50, v110
	v_mov_b32_e32 v223, v111
	v_lshlrev_b64 v[222:223], 1, v[222:223]
	v_lshl_add_u64 v[222:223], s[46:47], 0, v[222:223]
	global_load_dwordx2 v[216:217], v[222:223], off
	v_or_b32_e32 v222, 0x60, v110
	v_mov_b32_e32 v223, v111
	v_lshlrev_b64 v[222:223], 1, v[222:223]
	v_lshl_add_u64 v[222:223], s[46:47], 0, v[222:223]
	global_load_dwordx2 v[218:219], v[222:223], off
	v_or_b32_e32 v222, 0x70, v110
	v_mov_b32_e32 v223, v111
	v_lshlrev_b64 v[222:223], 1, v[222:223]
	v_lshl_add_u64 v[222:223], s[46:47], 0, v[222:223]
	global_load_dwordx2 v[220:221], v[222:223], off
	ds_bpermute_b32 v21, v70, v4
	v_xor_b32_e32 v14, 32, v238
	v_cmp_lt_i32_e32 vcc, v14, v20
	v_lshl_add_u64 v[16:17], s[48:49], 0, v[16:17]
	s_waitcnt lgkmcnt(0)
	v_add_f32_e32 v4, v4, v21
	v_cndmask_b32_e32 v14, v238, v14, vcc
	v_lshlrev_b32_e32 v71, 2, v14
	ds_bpermute_b32 v14, v71, v4
	s_waitcnt lgkmcnt(0)
	v_add_f32_e32 v4, v4, v14
	v_mul_f32_e32 v4, 0x3c000000, v4
	v_pk_add_f32 v[6:7], v[6:7], v[4:5] op_sel_hi:[1,0] neg_lo:[0,1] neg_hi:[0,1]
	v_pk_add_f32 v[8:9], v[8:9], v[4:5] op_sel_hi:[1,0] neg_lo:[0,1] neg_hi:[0,1]
	v_pk_mul_f32 v[36:37], v[6:7], v[6:7]
	v_pk_add_f32 v[14:15], v[0:1], v[4:5] op_sel_hi:[1,0] neg_lo:[0,1] neg_hi:[0,1]
	v_pk_add_f32 v[0:1], v[2:3], v[4:5] op_sel_hi:[1,0] neg_lo:[0,1] neg_hi:[0,1]
	v_pk_mul_f32 v[34:35], v[8:9], v[8:9]
	v_pk_add_f32 v[12:13], v[12:13], v[4:5] op_sel_hi:[1,0] neg_lo:[0,1] neg_hi:[0,1]
	v_pk_add_f32 v[10:11], v[10:11], v[4:5] op_sel_hi:[1,0] neg_lo:[0,1] neg_hi:[0,1]
	v_pk_add_f32 v[32:33], v[32:33], v[4:5] op_sel_hi:[1,0] neg_lo:[0,1] neg_hi:[0,1]
	v_pk_add_f32 v[30:31], v[30:31], v[4:5] op_sel_hi:[1,0] neg_lo:[0,1] neg_hi:[0,1]
	v_pk_add_f32 v[28:29], v[28:29], v[4:5] op_sel_hi:[1,0] neg_lo:[0,1] neg_hi:[0,1]
	v_pk_add_f32 v[26:27], v[26:27], v[4:5] op_sel_hi:[1,0] neg_lo:[0,1] neg_hi:[0,1]
	v_pk_add_f32 v[24:25], v[24:25], v[4:5] op_sel_hi:[1,0] neg_lo:[0,1] neg_hi:[0,1]
	v_pk_add_f32 v[22:23], v[22:23], v[4:5] op_sel_hi:[1,0] neg_lo:[0,1] neg_hi:[0,1]
	v_pk_add_f32 v[48:49], v[48:49], v[4:5] op_sel_hi:[1,0] neg_lo:[0,1] neg_hi:[0,1]
	v_pk_add_f32 v[46:47], v[46:47], v[4:5] op_sel_hi:[1,0] neg_lo:[0,1] neg_hi:[0,1]
	v_pk_add_f32 v[44:45], v[44:45], v[4:5] op_sel_hi:[1,0] neg_lo:[0,1] neg_hi:[0,1]
	v_pk_add_f32 v[42:43], v[42:43], v[4:5] op_sel_hi:[1,0] neg_lo:[0,1] neg_hi:[0,1]
	v_add_f32_e32 v4, v36, v37
	v_add_f32_e32 v4, v34, v4
	v_pk_mul_f32 v[40:41], v[10:11], v[10:11]
	v_add_f32_e32 v4, v35, v4
	v_add_f32_e32 v4, v40, v4
	v_pk_mul_f32 v[38:39], v[12:13], v[12:13]
	v_add_f32_e32 v4, v41, v4
	v_add_f32_e32 v4, v38, v4
	v_pk_mul_f32 v[52:53], v[30:31], v[30:31]
	v_add_f32_e32 v4, v39, v4
	v_add_f32_e32 v4, v52, v4
	v_pk_mul_f32 v[50:51], v[32:33], v[32:33]
	v_add_f32_e32 v4, v53, v4
	v_add_f32_e32 v4, v50, v4
	v_pk_mul_f32 v[56:57], v[26:27], v[26:27]
	v_add_f32_e32 v4, v51, v4
	v_add_f32_e32 v4, v56, v4
	v_pk_mul_f32 v[54:55], v[28:29], v[28:29]
	v_add_f32_e32 v4, v57, v4
	v_add_f32_e32 v4, v54, v4
	v_pk_mul_f32 v[60:61], v[22:23], v[22:23]
	v_add_f32_e32 v4, v55, v4
	v_add_f32_e32 v4, v60, v4
	v_pk_mul_f32 v[58:59], v[24:25], v[24:25]
	v_add_f32_e32 v4, v61, v4
	v_add_f32_e32 v4, v58, v4
	v_pk_mul_f32 v[64:65], v[46:47], v[46:47]
	v_add_f32_e32 v4, v59, v4
	v_add_f32_e32 v4, v64, v4
	v_pk_mul_f32 v[62:63], v[48:49], v[48:49]
	v_add_f32_e32 v4, v65, v4
	v_add_f32_e32 v4, v62, v4
	v_pk_mul_f32 v[68:69], v[42:43], v[42:43]
	v_add_f32_e32 v4, v63, v4
	v_add_f32_e32 v4, v68, v4
	v_pk_mul_f32 v[66:67], v[44:45], v[44:45]
	v_add_f32_e32 v4, v69, v4
	v_add_f32_e32 v4, v66, v4
	v_pk_mul_f32 v[20:21], v[14:15], v[14:15]
	v_add_f32_e32 v4, v67, v4
	v_add_f32_e32 v4, v20, v4
	v_pk_mul_f32 v[2:3], v[0:1], v[0:1]
	v_add_f32_e32 v4, v21, v4
	v_add_f32_e32 v2, v2, v4
	v_add_f32_e32 v4, v3, v2
	ds_bpermute_b32 v20, v70, v4
	s_waitcnt vmcnt(0)
	v_lshlrev_b32_e32 v2, 16, v18
	v_and_b32_e32 v3, 0xffff0000, v18
	v_lshlrev_b32_e32 v18, 16, v19
	v_and_b32_e32 v19, 0xffff0000, v19
	s_waitcnt lgkmcnt(0)
	v_add_f32_e32 v4, v4, v20
	ds_bpermute_b32 v21, v71, v4
	v_or_b32_e32 v20, 16, v110
	s_waitcnt lgkmcnt(0)
	v_add_f32_e32 v4, v4, v21
	v_fmamk_f32 v4, v4, 0x3c000000, v236
	v_mul_f32_e32 v21, 0x4b800000, v4
	v_cmp_gt_f32_e32 vcc, s0, v4
	s_nop 1
	v_cndmask_b32_e32 v4, v4, v21, vcc
	v_rsq_f32_e32 v4, v4
	v_mov_b32_e32 v21, v111
	v_lshlrev_b64 v[20:21], 1, v[20:21]
	v_lshl_add_u64 v[34:35], s[46:47], 0, v[20:21]
	v_mul_f32_e32 v36, 0x45800000, v4
	v_cndmask_b32_e32 v4, v4, v36, vcc
	v_pk_mul_f32 v[6:7], v[6:7], v[4:5] op_sel_hi:[1,0]
	v_pk_mul_f32 v[10:11], v[10:11], v[4:5] op_sel_hi:[1,0]
	v_pk_mul_f32 v[2:3], v[6:7], v[2:3]
	v_pk_mul_f32 v[6:7], v[8:9], v[4:5] op_sel_hi:[1,0]
	v_cvt_pk_bf16_f32 v2, v2, v3
	v_pk_mul_f32 v[6:7], v[6:7], v[18:19]
	v_pk_mul_f32 v[12:13], v[12:13], v[4:5] op_sel_hi:[1,0]
	v_cvt_pk_bf16_f32 v3, v6, v7
	global_store_dwordx2 v[16:17], v[2:3], off
	v_mov_b64_e32 v[2:3], v[208:209]
	v_mov_b32_e32 v7, v111
	v_or_b32_e32 v6, 32, v110
	v_lshlrev_b64 v[6:7], 1, v[6:7]
	v_lshl_add_u64 v[8:9], s[48:49], 0, v[20:21]
	v_lshl_add_u64 v[16:17], s[46:47], 0, v[6:7]
	v_lshl_add_u64 v[6:7], s[48:49], 0, v[6:7]
	v_pk_mul_f32 v[0:1], v[0:1], v[4:5] op_sel_hi:[1,0]
	v_lshlrev_b32_e32 v18, 16, v2
	v_and_b32_e32 v19, 0xffff0000, v2
	v_lshlrev_b32_e32 v2, 16, v3
	v_and_b32_e32 v3, 0xffff0000, v3
	v_pk_mul_f32 v[10:11], v[10:11], v[18:19]
	v_pk_mul_f32 v[2:3], v[12:13], v[2:3]
	v_cvt_pk_bf16_f32 v10, v10, v11
	v_cvt_pk_bf16_f32 v11, v2, v3
	global_store_dwordx2 v[8:9], v[10:11], off
	v_mov_b64_e32 v[2:3], v[210:211]
	v_pk_mul_f32 v[12:13], v[30:31], v[4:5] op_sel_hi:[1,0]
	v_pk_mul_f32 v[16:17], v[32:33], v[4:5] op_sel_hi:[1,0]
	v_mov_b32_e32 v9, v111
	v_or_b32_e32 v8, 48, v110
	v_lshlrev_b64 v[8:9], 1, v[8:9]
	v_lshl_add_u64 v[10:11], s[46:47], 0, v[8:9]
	v_lshl_add_u64 v[8:9], s[48:49], 0, v[8:9]
	v_lshlrev_b32_e32 v18, 16, v2
	v_and_b32_e32 v19, 0xffff0000, v2
	v_lshlrev_b32_e32 v2, 16, v3
	v_and_b32_e32 v3, 0xffff0000, v3
	v_pk_mul_f32 v[12:13], v[12:13], v[18:19]
	v_pk_mul_f32 v[2:3], v[16:17], v[2:3]
	v_cvt_pk_bf16_f32 v12, v12, v13
	v_cvt_pk_bf16_f32 v13, v2, v3
	global_store_dwordx2 v[6:7], v[12:13], off
	v_mov_b64_e32 v[2:3], v[212:213]
	v_pk_mul_f32 v[12:13], v[26:27], v[4:5] op_sel_hi:[1,0]
	v_pk_mul_f32 v[16:17], v[28:29], v[4:5] op_sel_hi:[1,0]
	v_mov_b32_e32 v7, v111
	v_or_b32_e32 v6, 64, v110
	v_lshlrev_b64 v[6:7], 1, v[6:7]
	v_lshl_add_u64 v[10:11], s[46:47], 0, v[6:7]
	v_lshl_add_u64 v[6:7], s[48:49], 0, v[6:7]
	v_lshlrev_b32_e32 v18, 16, v2
	v_and_b32_e32 v19, 0xffff0000, v2
	v_lshlrev_b32_e32 v2, 16, v3
	v_and_b32_e32 v3, 0xffff0000, v3
	v_pk_mul_f32 v[12:13], v[12:13], v[18:19]
	v_pk_mul_f32 v[2:3], v[16:17], v[2:3]
	v_cvt_pk_bf16_f32 v12, v12, v13
	v_cvt_pk_bf16_f32 v13, v2, v3
	global_store_dwordx2 v[8:9], v[12:13], off
	v_mov_b64_e32 v[2:3], v[214:215]
	v_pk_mul_f32 v[12:13], v[22:23], v[4:5] op_sel_hi:[1,0]
	v_pk_mul_f32 v[16:17], v[24:25], v[4:5] op_sel_hi:[1,0]
	v_mov_b32_e32 v9, v111
	v_or_b32_e32 v8, 0x50, v110
	v_lshlrev_b64 v[8:9], 1, v[8:9]
	v_lshl_add_u64 v[10:11], s[46:47], 0, v[8:9]
	v_lshl_add_u64 v[8:9], s[48:49], 0, v[8:9]
	v_lshlrev_b32_e32 v18, 16, v2
	v_and_b32_e32 v19, 0xffff0000, v2
	v_lshlrev_b32_e32 v2, 16, v3
	v_and_b32_e32 v3, 0xffff0000, v3
	v_pk_mul_f32 v[12:13], v[12:13], v[18:19]
	v_pk_mul_f32 v[2:3], v[16:17], v[2:3]
	v_cvt_pk_bf16_f32 v12, v12, v13
	v_cvt_pk_bf16_f32 v13, v2, v3
	global_store_dwordx2 v[6:7], v[12:13], off
	v_mov_b64_e32 v[2:3], v[216:217]
	v_pk_mul_f32 v[12:13], v[46:47], v[4:5] op_sel_hi:[1,0]
	v_pk_mul_f32 v[16:17], v[48:49], v[4:5] op_sel_hi:[1,0]
	v_mov_b32_e32 v7, v111
	v_or_b32_e32 v6, 0x60, v110
	v_lshlrev_b64 v[6:7], 1, v[6:7]
	v_lshl_add_u64 v[10:11], s[46:47], 0, v[6:7]
	v_or_b32_e32 v110, 0x70, v110
	v_lshl_add_u64 v[6:7], s[48:49], 0, v[6:7]
	v_lshlrev_b32_e32 v18, 16, v2
	v_and_b32_e32 v19, 0xffff0000, v2
	v_lshlrev_b32_e32 v2, 16, v3
	v_and_b32_e32 v3, 0xffff0000, v3
	v_pk_mul_f32 v[12:13], v[12:13], v[18:19]
	v_pk_mul_f32 v[2:3], v[16:17], v[2:3]
	v_cvt_pk_bf16_f32 v12, v12, v13
	v_cvt_pk_bf16_f32 v13, v2, v3
	global_store_dwordx2 v[8:9], v[12:13], off
	v_mov_b64_e32 v[2:3], v[218:219]
	v_pk_mul_f32 v[12:13], v[42:43], v[4:5] op_sel_hi:[1,0]
	v_pk_mul_f32 v[16:17], v[44:45], v[4:5] op_sel_hi:[1,0]
	v_lshlrev_b64 v[8:9], 1, v[110:111]
	v_lshl_add_u64 v[10:11], s[46:47], 0, v[8:9]
	v_lshlrev_b32_e32 v18, 16, v2
	v_and_b32_e32 v19, 0xffff0000, v2
	v_lshlrev_b32_e32 v2, 16, v3
	v_and_b32_e32 v3, 0xffff0000, v3
	v_pk_mul_f32 v[12:13], v[12:13], v[18:19]
	v_pk_mul_f32 v[2:3], v[16:17], v[2:3]
	v_cvt_pk_bf16_f32 v12, v12, v13
	v_cvt_pk_bf16_f32 v13, v2, v3
	global_store_dwordx2 v[6:7], v[12:13], off
	v_mov_b64_e32 v[2:3], v[220:221]
	v_pk_mul_f32 v[6:7], v[14:15], v[4:5] op_sel_hi:[1,0]
	v_lshlrev_b32_e32 v10, 16, v2
	v_and_b32_e32 v11, 0xffff0000, v2
	v_lshlrev_b32_e32 v2, 16, v3
	v_and_b32_e32 v3, 0xffff0000, v3
	v_pk_mul_f32 v[6:7], v[6:7], v[10:11]
	v_pk_mul_f32 v[0:1], v[0:1], v[2:3]
	v_cvt_pk_bf16_f32 v2, v6, v7
	v_cvt_pk_bf16_f32 v3, v0, v1
	v_lshl_add_u64 v[0:1], s[48:49], 0, v[8:9]
	global_store_dwordx2 v[0:1], v[2:3], off
